# attnC: V tile global loads moved from the softmax phase into the S phase (right after the previous V tile's LDS write); K LDS-write waits recounted (on top of v49)
# speedup vs baseline: 1.0043x; 1.0043x over previous
.LBB0_1087:
	s_and_b32 s61, s60, 1
	s_xor_b32 s62, s61, 1
	s_mulk_i32 s61, 0x4800
	s_mulk_i32 s62, 0x4800
	v_add_u32_e32 v233, s61, v128
	v_add_u32_e32 v234, s62, v152
	s_waitcnt vmcnt(0) lgkmcnt(0)
	s_barrier
	ds_read_b128 a[144:147], v233
	ds_read_b128 a[148:151], v233 offset:32
	ds_read_b128 a[152:155], v233 offset:64
	ds_read_b128 a[156:159], v233 offset:96
	s_waitcnt lgkmcnt(3)
	v_mfma_f32_32x32x16_bf16 v[188:203], a[144:147], v[28:31], v[32:47]
	s_cmp_eq_u32 s60, 0
	s_cselect_b32 s32, 0x9000, s61
	v_add3_u32 v224, s32, v153, v134
	v_add3_u32 v230, s32, v158, v134
	v_add3_u32 v231, s32, v159, v134
	v_mfma_f32_32x32x16_bf16 v[172:187], a[144:147], v[12:15], v[32:47]
	v_add3_u32 v232, s32, v160, v134
	ds_write_b128 v224, v[140:143] offset:36864
	ds_write_b128 v230, v[144:147] offset:36864
	ds_write_b128 v231, v[220:223] offset:36864
	ds_read_b128 a[144:147], v233 offset:4608
	s_waitcnt lgkmcnt(6)
	v_mfma_f32_32x32x16_bf16 v[188:203], a[148:151], v[24:27], v[188:203]
	ds_write_b128 v232, v[226:229] offset:36864
	v_lshl_add_u64 v[98:99], v[82:83], 0, v[156:157]
	global_load_dwordx4 v[64:67], v[98:99], off
	v_lshl_add_u64 v[98:99], v[84:85], 0, v[156:157]
	v_mfma_f32_32x32x16_bf16 v[172:187], a[148:151], v[8:11], v[172:187]
	global_load_dwordx4 v[68:71], v[98:99], off
	v_lshl_add_u64 v[98:99], v[86:87], 0, v[156:157]
	global_load_dwordx4 v[72:75], v[98:99], off
	v_lshl_add_u64 v[98:99], v[88:89], 0, v[156:157]
	ds_read_b128 a[148:151], v233 offset:4640
	s_waitcnt lgkmcnt(7)
	v_mfma_f32_32x32x16_bf16 v[188:203], a[152:155], v[20:23], v[188:203]
	global_load_dwordx4 v[76:79], v[98:99], off
	v_lshl_add_u64 v[98:99], v[90:91], 0, v[156:157]
	global_load_dwordx4 v[140:143], v[98:99], off
	v_lshl_add_u64 v[98:99], v[92:93], 0, v[156:157]
	v_mfma_f32_32x32x16_bf16 v[172:187], a[152:155], v[4:7], v[172:187]
	global_load_dwordx4 v[144:147], v[98:99], off
	v_lshl_add_u64 v[98:99], v[94:95], 0, v[156:157]
	global_load_dwordx4 v[220:223], v[98:99], off
	v_lshl_add_u64 v[98:99], v[96:97], 0, v[156:157]
	ds_read_b128 a[152:155], v233 offset:4672
	s_waitcnt lgkmcnt(7)
	v_mfma_f32_32x32x16_bf16 v[188:203], a[156:159], v[16:19], v[188:203]
	global_load_dwordx4 v[226:229], v[98:99], off
	v_lshl_add_u64 v[90:91], v[90:91], 0, s[56:57]
	v_lshl_add_u64 v[92:93], v[92:93], 0, s[56:57]
	v_lshl_add_u64 v[94:95], v[94:95], 0, s[56:57]
	v_mfma_f32_32x32x16_bf16 v[172:187], a[156:159], v[0:3], v[172:187]
	v_lshl_add_u64 v[96:97], v[96:97], 0, s[56:57]
	v_accvgpr_write_b32 a160, v48
	v_accvgpr_write_b32 a161, v49
	v_accvgpr_write_b32 a162, v50
	ds_read_b128 a[156:159], v233 offset:4704
	s_waitcnt lgkmcnt(4)
	v_mfma_f32_32x32x16_bf16 v[204:219], a[144:147], v[28:31], v[32:47]
	v_accvgpr_write_b32 a163, v51
	v_accvgpr_write_b32 a164, v52
	v_accvgpr_write_b32 a165, v53
	v_accvgpr_write_b32 a166, v54
	v_accvgpr_write_b32 a167, v55
	v_mfma_f32_32x32x16_bf16 v[100:115], a[144:147], v[12:15], v[32:47]
	v_accvgpr_write_b32 a168, v56
	v_accvgpr_write_b32 a169, v57
	v_accvgpr_write_b32 a170, v58
	v_accvgpr_write_b32 a171, v59
	s_waitcnt lgkmcnt(2)
	v_mfma_f32_32x32x16_bf16 v[204:219], a[148:151], v[24:27], v[204:219]
	v_accvgpr_write_b32 a172, v60
	v_accvgpr_write_b32 a173, v61
	v_accvgpr_write_b32 a174, v62
	v_accvgpr_write_b32 a175, v63
	v_mfma_f32_32x32x16_bf16 v[100:115], a[148:151], v[8:11], v[100:115]
	v_accvgpr_write_b32 a176, v116
	v_accvgpr_write_b32 a177, v117
	v_accvgpr_write_b32 a178, v118
	v_accvgpr_write_b32 a179, v119
	s_waitcnt lgkmcnt(1)
	v_mfma_f32_32x32x16_bf16 v[204:219], a[152:155], v[20:23], v[204:219]
	v_accvgpr_write_b32 a180, v120
	v_accvgpr_write_b32 a181, v121
	v_accvgpr_write_b32 a182, v122
	v_accvgpr_write_b32 a183, v123
	v_mfma_f32_32x32x16_bf16 v[100:115], a[152:155], v[4:7], v[100:115]
	v_accvgpr_write_b32 a184, v124
	v_accvgpr_write_b32 a185, v125
	v_accvgpr_write_b32 a186, v126
	v_accvgpr_write_b32 a187, v127
	s_waitcnt lgkmcnt(0)
	v_mfma_f32_32x32x16_bf16 v[204:219], a[156:159], v[16:19], v[204:219]
	v_accvgpr_write_b32 a188, v130
	v_accvgpr_write_b32 a189, v131
	v_accvgpr_write_b32 a190, v132
	v_accvgpr_write_b32 a191, v133
	v_mfma_f32_32x32x16_bf16 v[100:115], a[156:159], v[0:3], v[100:115]
	v_lshl_add_u64 v[82:83], v[82:83], 0, s[54:55]
	v_lshl_add_u64 v[84:85], v[84:85], 0, s[54:55]
	v_lshl_add_u64 v[86:87], v[86:87], 0, s[54:55]
	v_lshl_add_u64 v[88:89], v[88:89], 0, s[54:55]
	ds_read_b128 a[144:147], v234 offset:36864
	ds_read_b128 a[148:151], v234 offset:36896
	ds_read_b128 a[152:155], v234 offset:36928
	ds_read_b128 a[156:159], v234 offset:36960
	s_waitcnt lgkmcnt(3)
	v_mfma_f32_32x32x16_bf16 a[128:143], a[144:147], a[160:163], a[128:143]
	v_exp_f32_e32 v188, v188
	v_exp_f32_e32 v189, v189
	v_exp_f32_e32 v190, v190
	v_mfma_f32_32x32x16_bf16 a[112:127], a[144:147], a[176:179], a[112:127]
	v_exp_f32_e32 v191, v191
	v_exp_f32_e32 v192, v192
	v_exp_f32_e32 v193, v193
	v_exp_f32_e32 v194, v194
	ds_read_b128 a[144:147], v234 offset:41472
	s_waitcnt lgkmcnt(3)
	v_mfma_f32_32x32x16_bf16 a[128:143], a[148:151], a[164:167], a[128:143]
	v_exp_f32_e32 v195, v195
	v_exp_f32_e32 v196, v196
	v_exp_f32_e32 v197, v197
	v_mfma_f32_32x32x16_bf16 a[112:127], a[148:151], a[180:183], a[112:127]
	v_exp_f32_e32 v198, v198
	v_exp_f32_e32 v199, v199
	v_exp_f32_e32 v200, v200
	v_exp_f32_e32 v201, v201
	ds_read_b128 a[148:151], v234 offset:41504
	s_waitcnt lgkmcnt(3)
	v_mfma_f32_32x32x16_bf16 a[128:143], a[152:155], a[168:171], a[128:143]
	v_exp_f32_e32 v202, v202
	v_exp_f32_e32 v203, v203
	v_pk_add_f32 v[136:137], v[188:189], v[190:191]
	v_pk_add_f32 v[136:137], v[136:137], v[192:193]
	v_mfma_f32_32x32x16_bf16 a[112:127], a[152:155], a[184:187], a[112:127]
	v_pk_add_f32 v[136:137], v[136:137], v[194:195]
	v_pk_add_f32 v[136:137], v[136:137], v[196:197]
	v_pk_add_f32 v[136:137], v[136:137], v[198:199]
	ds_read_b128 a[152:155], v234 offset:41536
	s_waitcnt lgkmcnt(3)
	v_mfma_f32_32x32x16_bf16 a[128:143], a[156:159], a[172:175], a[128:143]
	v_pk_add_f32 v[136:137], v[136:137], v[200:201]
	v_pk_add_f32 v[136:137], v[136:137], v[202:203]
	v_cvt_pk_bf16_f32 v48, v188, v189
	v_cvt_pk_bf16_f32 v49, v190, v191
	v_cvt_pk_bf16_f32 v50, v192, v193
	v_cvt_pk_bf16_f32 v51, v194, v195
	v_cvt_pk_bf16_f32 v52, v196, v197
	v_mfma_f32_32x32x16_bf16 a[112:127], a[156:159], a[188:191], a[112:127]
	v_cvt_pk_bf16_f32 v53, v198, v199
	v_cvt_pk_bf16_f32 v54, v200, v201
	v_cvt_pk_bf16_f32 v55, v202, v203
	v_add3_u32 v224, s62, v153, v134
	v_add3_u32 v230, s62, v158, v134
	s_waitcnt vmcnt(7)
	ds_write_b128 v224, v[64:67]
	s_waitcnt vmcnt(6)
	ds_read_b128 a[156:159], v234 offset:41568
	s_waitcnt lgkmcnt(4)
	v_mfma_f32_32x32x16_bf16 a[48:63], a[144:147], a[160:163], a[48:63]
	ds_write_b128 v230, v[68:71]
	s_waitcnt vmcnt(5)
	ds_write_b128 v224, v[72:75] offset:9216
	s_waitcnt vmcnt(4)
	ds_write_b128 v230, v[76:79] offset:9216
	v_mfma_f32_32x32x16_bf16 a[64:79], a[144:147], a[176:179], a[64:79]
	v_exp_f32_e32 v172, v172
	v_exp_f32_e32 v173, v173
	v_exp_f32_e32 v174, v174
	v_exp_f32_e32 v175, v175
	ds_read_b128 a[144:147], v234 offset:46080
	s_waitcnt lgkmcnt(7)
	v_mfma_f32_32x32x16_bf16 a[48:63], a[148:151], a[164:167], a[48:63]
	v_exp_f32_e32 v176, v176
	v_exp_f32_e32 v177, v177
	v_exp_f32_e32 v178, v178
	v_exp_f32_e32 v179, v179
	v_mfma_f32_32x32x16_bf16 a[64:79], a[148:151], a[180:183], a[64:79]
	v_exp_f32_e32 v180, v180
	v_exp_f32_e32 v181, v181
	v_exp_f32_e32 v182, v182
	ds_read_b128 a[148:151], v234 offset:46112
	s_waitcnt lgkmcnt(7)
	v_mfma_f32_32x32x16_bf16 a[48:63], a[152:155], a[168:171], a[48:63]
	v_exp_f32_e32 v183, v183
	v_exp_f32_e32 v184, v184
	v_exp_f32_e32 v185, v185
	v_exp_f32_e32 v186, v186
	v_mfma_f32_32x32x16_bf16 a[64:79], a[152:155], a[184:187], a[64:79]
	v_exp_f32_e32 v187, v187
	v_pk_add_f32 v[148:149], v[172:173], v[174:175]
	v_pk_add_f32 v[148:149], v[148:149], v[176:177]
	v_pk_add_f32 v[148:149], v[148:149], v[178:179]
	ds_read_b128 a[152:155], v234 offset:46144
	s_waitcnt lgkmcnt(6)
	v_mfma_f32_32x32x16_bf16 a[48:63], a[156:159], a[172:175], a[48:63]
	v_pk_add_f32 v[148:149], v[148:149], v[180:181]
	v_pk_add_f32 v[148:149], v[148:149], v[182:183]
	v_pk_add_f32 v[148:149], v[148:149], v[184:185]
	v_mfma_f32_32x32x16_bf16 a[64:79], a[156:159], a[188:191], a[64:79]
	v_pk_add_f32 v[148:149], v[148:149], v[186:187]
	v_cvt_pk_bf16_f32 v116, v172, v173
	v_cvt_pk_bf16_f32 v117, v174, v175
	v_cvt_pk_bf16_f32 v118, v176, v177
	v_cvt_pk_bf16_f32 v119, v178, v179
	v_cvt_pk_bf16_f32 v120, v180, v181
	v_cvt_pk_bf16_f32 v121, v182, v183
	v_cvt_pk_bf16_f32 v122, v184, v185
	ds_read_b128 a[156:159], v234 offset:46176
	s_waitcnt lgkmcnt(3)
	v_mfma_f32_32x32x16_bf16 a[80:95], a[144:147], a[160:163], a[80:95]
	v_cvt_pk_bf16_f32 v123, v186, v187
	v_exp_f32_e32 v204, v204
	v_exp_f32_e32 v205, v205
	v_exp_f32_e32 v206, v206
	v_mfma_f32_32x32x16_bf16 a[96:111], a[144:147], a[176:179], a[96:111]
	v_exp_f32_e32 v207, v207
	v_exp_f32_e32 v208, v208
	v_exp_f32_e32 v209, v209
	ds_read_b128 a[144:147], v234 offset:50688
	s_waitcnt lgkmcnt(3)
	v_mfma_f32_32x32x16_bf16 a[80:95], a[148:151], a[164:167], a[80:95]
	v_exp_f32_e32 v210, v210
	v_exp_f32_e32 v211, v211
	v_exp_f32_e32 v212, v212
	v_exp_f32_e32 v213, v213
	v_mfma_f32_32x32x16_bf16 a[96:111], a[148:151], a[180:183], a[96:111]
	v_exp_f32_e32 v214, v214
	v_exp_f32_e32 v215, v215
	v_exp_f32_e32 v216, v216
	v_exp_f32_e32 v217, v217
	ds_read_b128 a[148:151], v234 offset:50720
	s_waitcnt lgkmcnt(3)
	v_mfma_f32_32x32x16_bf16 a[80:95], a[152:155], a[168:171], a[80:95]
	v_exp_f32_e32 v218, v218
	v_exp_f32_e32 v219, v219
	v_pk_add_f32 v[136:137], v[136:137], v[204:205]
	v_mfma_f32_32x32x16_bf16 a[96:111], a[152:155], a[184:187], a[96:111]
	v_pk_add_f32 v[136:137], v[136:137], v[206:207]
	v_pk_add_f32 v[136:137], v[136:137], v[208:209]
	v_pk_add_f32 v[136:137], v[136:137], v[210:211]
	v_pk_add_f32 v[136:137], v[136:137], v[212:213]
	ds_read_b128 a[152:155], v234 offset:50752
	s_waitcnt lgkmcnt(3)
	v_mfma_f32_32x32x16_bf16 a[80:95], a[156:159], a[172:175], a[80:95]
	v_pk_add_f32 v[136:137], v[136:137], v[214:215]
	v_pk_add_f32 v[136:137], v[136:137], v[216:217]
	v_pk_add_f32 v[136:137], v[136:137], v[218:219]
	v_cvt_pk_bf16_f32 v56, v204, v205
	v_cvt_pk_bf16_f32 v57, v206, v207
	v_mfma_f32_32x32x16_bf16 a[96:111], a[156:159], a[188:191], a[96:111]
	v_cvt_pk_bf16_f32 v58, v208, v209
	v_cvt_pk_bf16_f32 v59, v210, v211
	v_cvt_pk_bf16_f32 v60, v212, v213
	v_cvt_pk_bf16_f32 v61, v214, v215
	v_cvt_pk_bf16_f32 v62, v216, v217
	v_cvt_pk_bf16_f32 v63, v218, v219
	v_add_f32_e32 v235, v136, v137
	ds_read_b128 a[156:159], v234 offset:50784
	s_waitcnt lgkmcnt(3)
	v_mfma_f32_32x32x16_bf16 a[32:47], a[144:147], a[160:163], a[32:47]
	v_add_f32_e32 v81, v81, v235
	v_exp_f32_e32 v100, v100
	v_exp_f32_e32 v101, v101
	v_exp_f32_e32 v102, v102
	v_mfma_f32_32x32x16_bf16 a[16:31], a[144:147], a[176:179], a[16:31]
	v_exp_f32_e32 v103, v103
	v_exp_f32_e32 v104, v104
	v_exp_f32_e32 v105, v105
	v_exp_f32_e32 v106, v106
	s_waitcnt lgkmcnt(2)
	v_mfma_f32_32x32x16_bf16 a[32:47], a[148:151], a[164:167], a[32:47]
	v_exp_f32_e32 v107, v107
	v_exp_f32_e32 v108, v108
	v_exp_f32_e32 v109, v109
	v_mfma_f32_32x32x16_bf16 a[16:31], a[148:151], a[180:183], a[16:31]
	v_exp_f32_e32 v110, v110
	v_exp_f32_e32 v111, v111
	v_exp_f32_e32 v112, v112
	v_exp_f32_e32 v113, v113
	s_waitcnt lgkmcnt(1)
	v_mfma_f32_32x32x16_bf16 a[32:47], a[152:155], a[168:171], a[32:47]
	v_exp_f32_e32 v114, v114
	v_exp_f32_e32 v115, v115
	v_pk_add_f32 v[148:149], v[148:149], v[100:101]
	v_pk_add_f32 v[148:149], v[148:149], v[102:103]
	v_mfma_f32_32x32x16_bf16 a[16:31], a[152:155], a[184:187], a[16:31]
	v_pk_add_f32 v[148:149], v[148:149], v[104:105]
	v_pk_add_f32 v[148:149], v[148:149], v[106:107]
	v_pk_add_f32 v[148:149], v[148:149], v[108:109]
	s_waitcnt lgkmcnt(0)
	v_mfma_f32_32x32x16_bf16 a[32:47], a[156:159], a[172:175], a[32:47]
	v_pk_add_f32 v[148:149], v[148:149], v[110:111]
	v_pk_add_f32 v[148:149], v[148:149], v[112:113]
	v_pk_add_f32 v[148:149], v[148:149], v[114:115]
	v_cvt_pk_bf16_f32 v124, v100, v101
	v_cvt_pk_bf16_f32 v125, v102, v103
	v_mfma_f32_32x32x16_bf16 a[16:31], a[156:159], a[188:191], a[16:31]
	v_cvt_pk_bf16_f32 v126, v104, v105
	v_cvt_pk_bf16_f32 v127, v106, v107
	v_cvt_pk_bf16_f32 v130, v108, v109
	v_cvt_pk_bf16_f32 v131, v110, v111
	v_cvt_pk_bf16_f32 v132, v112, v113
	v_cvt_pk_bf16_f32 v133, v114, v115
	v_add_f32_e32 v235, v148, v149
	v_add_f32_e32 v80, v80, v235
	s_add_i32 s60, s60, 1
	s_cmp_eq_u32 s8, s60
	s_cbranch_scc0 .LBB0_1087
	s_waitcnt vmcnt(0) lgkmcnt(0)
	s_barrier
	v_add3_u32 v224, s62, v153, v134
	v_add3_u32 v230, s62, v158, v134
	v_add3_u32 v231, s62, v159, v134
	v_add3_u32 v232, s62, v160, v134
	ds_write_b128 v224, v[140:143] offset:36864
	ds_write_b128 v230, v[144:147] offset:36864
	ds_write_b128 v231, v[220:223] offset:36864
	ds_write_b128 v232, v[226:229] offset:36864
	v_add_u32_e32 v234, s61, v152
	ds_read_b128 a[144:147], v234 offset:36864
	ds_read_b128 a[148:151], v234 offset:36896
	ds_read_b128 a[152:155], v234 offset:36928
	ds_read_b128 a[156:159], v234 offset:36960
	s_waitcnt lgkmcnt(3)
	v_mfma_f32_32x32x16_bf16 a[128:143], a[144:147], v[48:51], a[128:143]
	v_mfma_f32_32x32x16_bf16 a[112:127], a[144:147], v[116:119], a[112:127]
	ds_read_b128 a[144:147], v234 offset:41472
	s_waitcnt lgkmcnt(3)
	v_mfma_f32_32x32x16_bf16 a[128:143], a[148:151], v[52:55], a[128:143]
	v_mfma_f32_32x32x16_bf16 a[112:127], a[148:151], v[120:123], a[112:127]
	ds_read_b128 a[148:151], v234 offset:41504
	s_waitcnt lgkmcnt(3)
	v_mfma_f32_32x32x16_bf16 a[128:143], a[152:155], v[56:59], a[128:143]
	v_mfma_f32_32x32x16_bf16 a[112:127], a[152:155], v[124:127], a[112:127]
	ds_read_b128 a[152:155], v234 offset:41536
	s_waitcnt lgkmcnt(3)
	v_mfma_f32_32x32x16_bf16 a[128:143], a[156:159], v[60:63], a[128:143]
	v_mfma_f32_32x32x16_bf16 a[112:127], a[156:159], v[130:133], a[112:127]
	ds_read_b128 a[156:159], v234 offset:41568
	s_waitcnt lgkmcnt(3)
	v_mfma_f32_32x32x16_bf16 a[48:63], a[144:147], v[48:51], a[48:63]
	v_mfma_f32_32x32x16_bf16 a[64:79], a[144:147], v[116:119], a[64:79]
	ds_read_b128 a[144:147], v234 offset:46080
	s_waitcnt lgkmcnt(3)
	v_mfma_f32_32x32x16_bf16 a[48:63], a[148:151], v[52:55], a[48:63]
	v_mfma_f32_32x32x16_bf16 a[64:79], a[148:151], v[120:123], a[64:79]
	ds_read_b128 a[148:151], v234 offset:46112
	s_waitcnt lgkmcnt(3)
	v_mfma_f32_32x32x16_bf16 a[48:63], a[152:155], v[56:59], a[48:63]
	v_mfma_f32_32x32x16_bf16 a[64:79], a[152:155], v[124:127], a[64:79]
	ds_read_b128 a[152:155], v234 offset:46144
	s_waitcnt lgkmcnt(3)
	v_mfma_f32_32x32x16_bf16 a[48:63], a[156:159], v[60:63], a[48:63]
	v_mfma_f32_32x32x16_bf16 a[64:79], a[156:159], v[130:133], a[64:79]
	ds_read_b128 a[156:159], v234 offset:46176
	s_waitcnt lgkmcnt(3)
	v_mfma_f32_32x32x16_bf16 a[80:95], a[144:147], v[48:51], a[80:95]
	v_mfma_f32_32x32x16_bf16 a[96:111], a[144:147], v[116:119], a[96:111]
	ds_read_b128 a[144:147], v234 offset:50688
	s_waitcnt lgkmcnt(3)
	v_mfma_f32_32x32x16_bf16 a[80:95], a[148:151], v[52:55], a[80:95]
	v_mfma_f32_32x32x16_bf16 a[96:111], a[148:151], v[120:123], a[96:111]
	ds_read_b128 a[148:151], v234 offset:50720
	s_waitcnt lgkmcnt(3)
	v_mfma_f32_32x32x16_bf16 a[80:95], a[152:155], v[56:59], a[80:95]
	v_mfma_f32_32x32x16_bf16 a[96:111], a[152:155], v[124:127], a[96:111]
	ds_read_b128 a[152:155], v234 offset:50752
	s_waitcnt lgkmcnt(3)
	v_mfma_f32_32x32x16_bf16 a[80:95], a[156:159], v[60:63], a[80:95]
	v_mfma_f32_32x32x16_bf16 a[96:111], a[156:159], v[130:133], a[96:111]
	ds_read_b128 a[156:159], v234 offset:50784
	s_waitcnt lgkmcnt(3)
	v_mfma_f32_32x32x16_bf16 a[32:47], a[144:147], v[48:51], a[32:47]
	v_mfma_f32_32x32x16_bf16 a[16:31], a[144:147], v[116:119], a[16:31]
	s_waitcnt lgkmcnt(2)
	v_mfma_f32_32x32x16_bf16 a[32:47], a[148:151], v[52:55], a[32:47]
	v_mfma_f32_32x32x16_bf16 a[16:31], a[148:151], v[120:123], a[16:31]
	s_waitcnt lgkmcnt(1)
	v_mfma_f32_32x32x16_bf16 a[32:47], a[152:155], v[56:59], a[32:47]
	v_mfma_f32_32x32x16_bf16 a[16:31], a[152:155], v[124:127], a[16:31]
	s_waitcnt lgkmcnt(0)
	v_mfma_f32_32x32x16_bf16 a[32:47], a[156:159], v[60:63], a[32:47]
	v_mfma_f32_32x32x16_bf16 a[16:31], a[156:159], v[130:133], a[16:31]
	s_bitcmp1_b32 s8, 0
	s_cselect_b32 s8, 0x4800, 0
	v_add_u32_e32 v48, s8, v128
	s_waitcnt lgkmcnt(0)
	s_barrier
	ds_read_b128 v[32:35], v48
	ds_read_b128 v[36:39], v48 offset:32
	s_waitcnt lgkmcnt(1)
	v_mfma_f32_32x32x16_bf16 a[186:201], v[32:35], v[28:31], a[0:15]
	v_add_u32_e32 v83, s8, v152
	v_mfma_f32_32x32x16_bf16 a[144:159], v[32:35], v[12:15], a[0:15]
	s_waitcnt lgkmcnt(0)
	v_mfma_f32_32x32x16_bf16 a[186:201], v[36:39], v[24:27], a[186:201]
	v_mfma_f32_32x32x16_bf16 a[144:159], v[36:39], v[8:11], a[144:159]
	ds_read_b128 v[32:35], v48 offset:64
	ds_read_b128 v[36:39], v48 offset:96
	s_waitcnt lgkmcnt(1)
	v_mfma_f32_32x32x16_bf16 a[186:201], v[32:35], v[20:23], a[186:201]
	s_waitcnt lgkmcnt(0)
	v_mfma_f32_32x32x16_bf16 a[186:201], v[36:39], v[16:19], a[186:201]
	v_mfma_f32_32x32x16_bf16 a[144:159], v[32:35], v[4:7], a[144:159]
	ds_read_b128 v[32:35], v48 offset:4608
	ds_read_b128 v[40:43], v48 offset:4640
	ds_read_b128 v[44:47], v48 offset:4672
	ds_read_b128 v[48:51], v48 offset:4704
	s_nop 6
	v_accvgpr_read_b32 v52, a186
	v_accvgpr_read_b32 v53, a187
	v_accvgpr_read_b32 v54, a188
	v_exp_f32_e32 v52, v52
	v_exp_f32_e32 v53, v53
	s_waitcnt lgkmcnt(3)
	v_mfma_f32_32x32x16_bf16 a[172:187], v[32:35], v[28:31], a[0:15]
	v_accvgpr_read_b32 v28, a189
	v_exp_f32_e32 v55, v28
	v_accvgpr_read_b32 v28, a190
	v_exp_f32_e32 v56, v28
	v_accvgpr_read_b32 v28, a191
	v_exp_f32_e32 v54, v54
	v_exp_f32_e32 v57, v28
	s_waitcnt lgkmcnt(2)
	v_mfma_f32_32x32x16_bf16 a[172:187], v[40:43], v[24:27], a[172:187]
	v_accvgpr_read_b32 v24, a192
	v_exp_f32_e32 v58, v24
	v_accvgpr_read_b32 v24, a193
	v_exp_f32_e32 v59, v24
	v_accvgpr_read_b32 v24, a194
	v_exp_f32_e32 v60, v24
	v_accvgpr_read_b32 v24, a195
	s_waitcnt lgkmcnt(1)
	v_mfma_f32_32x32x16_bf16 a[172:187], v[44:47], v[20:23], a[172:187]
	v_accvgpr_read_b32 v20, a196
	v_exp_f32_e32 v62, v20
	v_accvgpr_read_b32 v20, a197
	v_exp_f32_e32 v63, v20
	v_accvgpr_read_b32 v20, a198
	v_exp_f32_e32 v64, v20
	v_exp_f32_e32 v61, v24
	s_waitcnt lgkmcnt(0)
	v_mfma_f32_32x32x16_bf16 a[172:187], v[48:51], v[16:19], a[172:187]
	v_accvgpr_read_b32 v16, a199
	v_exp_f32_e32 v65, v16
	v_accvgpr_read_b32 v16, a200
	v_exp_f32_e32 v66, v16
	v_accvgpr_read_b32 v16, a201
	v_exp_f32_e32 v67, v16
	ds_read_b128 v[28:31], v83 offset:36928
	v_mfma_f32_32x32x16_bf16 a[144:159], v[36:39], v[0:3], a[144:159]
	s_nop 3
	v_accvgpr_read_b32 v16, a172
	v_exp_f32_e32 v36, v16
	v_accvgpr_read_b32 v16, a173
	v_exp_f32_e32 v37, v16
	v_accvgpr_read_b32 v16, a174
	v_exp_f32_e32 v38, v16
	v_accvgpr_read_b32 v16, a175
	v_mfma_f32_32x32x16_bf16 a[160:175], v[32:35], v[12:15], a[0:15]
	v_exp_f32_e32 v39, v16
	v_accvgpr_read_b32 v16, a144
	v_accvgpr_read_b32 v12, a176
	v_exp_f32_e32 v68, v12
	v_accvgpr_read_b32 v12, a177
	v_accvgpr_read_b32 v20, a157
	v_exp_f32_e32 v69, v12
	v_mfma_f32_32x32x16_bf16 a[160:175], v[40:43], v[8:11], a[160:175]
	v_accvgpr_read_b32 v12, a178
	v_exp_f32_e32 v84, v20
	v_accvgpr_read_b32 v20, a158
	v_exp_f32_e32 v70, v12
	v_accvgpr_read_b32 v12, a179
	v_exp_f32_e32 v85, v20
	v_accvgpr_read_b32 v20, a159
	v_mfma_f32_32x32x16_bf16 a[160:175], v[44:47], v[4:7], a[160:175]
	v_exp_f32_e32 v40, v12
	v_cvt_pk_bf16_f32 v12, v52, v53
	v_cvt_pk_bf16_f32 v13, v54, v55
	v_cvt_pk_bf16_f32 v14, v56, v57
	v_cvt_pk_bf16_f32 v15, v58, v59
	v_exp_f32_e32 v86, v20
	ds_read_b128 v[20:23], v83 offset:36896
	v_mfma_f32_32x32x16_bf16 a[160:175], v[48:51], v[0:3], a[160:175]
	v_exp_f32_e32 v49, v16
	v_accvgpr_read_b32 v16, a145
	v_exp_f32_e32 v50, v16
	v_accvgpr_read_b32 v16, a146
	v_exp_f32_e32 v51, v16
	v_accvgpr_read_b32 v16, a147
	v_exp_f32_e32 v71, v16
	v_accvgpr_read_b32 v16, a148
	v_exp_f32_e32 v72, v16
	v_accvgpr_read_b32 v16, a149
	v_exp_f32_e32 v73, v16
	v_accvgpr_read_b32 v16, a150
	v_exp_f32_e32 v74, v16
	v_accvgpr_read_b32 v16, a151
	v_exp_f32_e32 v75, v16
	v_accvgpr_read_b32 v16, a152
	v_exp_f32_e32 v76, v16
	v_accvgpr_read_b32 v16, a153
	v_exp_f32_e32 v77, v16
	v_accvgpr_read_b32 v16, a154
	v_exp_f32_e32 v78, v16
	v_accvgpr_read_b32 v16, a155
	v_exp_f32_e32 v79, v16
	v_accvgpr_read_b32 v16, a156
	v_exp_f32_e32 v82, v16
	ds_read_b128 v[16:19], v83 offset:36864
	v_accvgpr_read_b32 v24, a160
	v_exp_f32_e32 v87, v24
	v_accvgpr_read_b32 v24, a161
	v_exp_f32_e32 v88, v24
	v_cvt_pk_bf16_f32 v24, v49, v50
	v_cvt_pk_bf16_f32 v25, v51, v71
	v_cvt_pk_bf16_f32 v26, v72, v73
	v_cvt_pk_bf16_f32 v27, v74, v75
	s_waitcnt lgkmcnt(0)
	v_mfma_f32_32x32x16_bf16 a[144:159], v[16:19], v[12:15], a[128:143]
	v_accvgpr_read_b32 v8, a180
	v_exp_f32_e32 v41, v8
	v_accvgpr_read_b32 v8, a181
	v_exp_f32_e32 v42, v8
	v_accvgpr_read_b32 v8, a182
	v_exp_f32_e32 v43, v8
	v_cvt_pk_bf16_f32 v8, v60, v61
	v_mfma_f32_32x32x16_bf16 a[128:143], v[16:19], v[24:27], a[112:127]
	v_accvgpr_read_b32 v16, a162
	v_exp_f32_e32 v89, v16
	v_accvgpr_read_b32 v16, a163
	v_exp_f32_e32 v90, v16
	v_accvgpr_read_b32 v16, a164
	v_exp_f32_e32 v91, v16
	v_accvgpr_read_b32 v16, a165
	v_cvt_pk_bf16_f32 v9, v62, v63
	v_cvt_pk_bf16_f32 v10, v64, v65
	v_cvt_pk_bf16_f32 v11, v66, v67
	v_exp_f32_e32 v92, v16
	v_cvt_pk_bf16_f32 v16, v76, v77
	v_cvt_pk_bf16_f32 v17, v78, v79
	v_cvt_pk_bf16_f32 v18, v82, v84
	v_cvt_pk_bf16_f32 v19, v85, v86
	v_mfma_f32_32x32x16_bf16 a[144:159], v[20:23], v[8:11], a[144:159]
	v_accvgpr_read_b32 v32, a166
	v_accvgpr_read_b32 v4, a183
	v_exp_f32_e32 v93, v32
	v_exp_f32_e32 v44, v4
	v_accvgpr_read_b32 v4, a184
	v_exp_f32_e32 v45, v4
	v_accvgpr_read_b32 v4, a185
	v_mfma_f32_32x32x16_bf16 a[128:143], v[20:23], v[16:19], a[128:143]
	v_accvgpr_read_b32 v20, a167
	v_exp_f32_e32 v94, v20
	v_accvgpr_read_b32 v32, a169
	v_exp_f32_e32 v46, v4
	v_accvgpr_read_b32 v4, a186
	v_exp_f32_e32 v96, v32
	v_accvgpr_read_b32 v32, a170
	v_exp_f32_e32 v47, v4
	v_cvt_pk_bf16_f32 v4, v36, v37
	v_cvt_pk_bf16_f32 v5, v38, v39
	v_cvt_pk_bf16_f32 v6, v68, v69
	v_cvt_pk_bf16_f32 v7, v70, v40
	v_accvgpr_read_b32 v20, a168
	v_exp_f32_e32 v97, v32
	v_cvt_pk_bf16_f32 v32, v87, v88
	v_cvt_pk_bf16_f32 v33, v89, v90
	v_cvt_pk_bf16_f32 v34, v91, v92
	v_cvt_pk_bf16_f32 v35, v93, v94
	v_exp_f32_e32 v95, v20
	ds_read_b128 v[20:23], v83 offset:36960
	v_mfma_f32_32x32x16_bf16 a[144:159], v[28:31], v[4:7], a[144:159]
	v_accvgpr_read_b32 v0, a187
	v_exp_f32_e32 v48, v0
	v_cvt_pk_bf16_f32 v0, v41, v42
	v_cvt_pk_bf16_f32 v1, v43, v44
	v_cvt_pk_bf16_f32 v2, v45, v46
	v_cvt_pk_bf16_f32 v3, v47, v48
	v_cvt_pk_bf16_f32 v130, v95, v96
	v_mfma_f32_32x32x16_bf16 a[128:143], v[28:31], v[32:35], a[128:143]
	v_accvgpr_read_b32 v28, a171
	v_exp_f32_e32 v98, v28
	v_accvgpr_read_b32 v28, a172
	v_exp_f32_e32 v99, v28
	v_accvgpr_read_b32 v28, a173
	v_exp_f32_e32 v100, v28
	v_accvgpr_read_b32 v28, a174
	v_exp_f32_e32 v101, v28
	v_accvgpr_read_b32 v28, a175
	v_exp_f32_e32 v102, v28
	v_cvt_pk_bf16_f32 v131, v97, v98
	v_cvt_pk_bf16_f32 v132, v99, v100
	s_waitcnt lgkmcnt(0)
	v_mfma_f32_32x32x16_bf16 a[144:159], v[20:23], v[0:3], a[144:159]
	v_cvt_pk_bf16_f32 v133, v101, v102
	s_nop 1
	v_mfma_f32_32x32x16_bf16 a[128:143], v[20:23], v[130:133], a[128:143]
	ds_read_b128 v[20:23], v83 offset:41472
	ds_read_b128 v[28:31], v83 offset:41504
	s_nop 5
	v_accvgpr_read_b32 v112, a144
	v_accvgpr_read_b32 v113, a145
	v_accvgpr_read_b32 v114, a146
	v_accvgpr_read_b32 v115, a147
	s_waitcnt lgkmcnt(1)
	v_mfma_f32_32x32x16_bf16 a[112:127], v[20:23], v[12:15], a[48:63]
	v_accvgpr_read_b32 v116, a148
	v_accvgpr_read_b32 v117, a149
	v_accvgpr_read_b32 v118, a150
	v_accvgpr_read_b32 v119, a151
	v_accvgpr_read_b32 v120, a152
	v_accvgpr_read_b32 v121, a153
	v_accvgpr_read_b32 v122, a154
	v_mfma_f32_32x32x16_bf16 a[48:63], v[20:23], v[24:27], a[64:79]
	v_accvgpr_read_b32 v123, a155
	v_accvgpr_read_b32 v124, a156
	v_accvgpr_read_b32 v125, a157
	v_accvgpr_read_b32 v126, a158
	v_accvgpr_read_b32 v127, a159
	s_waitcnt lgkmcnt(0)
	v_mfma_f32_32x32x16_bf16 a[112:127], v[28:31], v[8:11], a[112:127]
	v_mfma_f32_32x32x16_bf16 a[48:63], v[28:31], v[16:19], a[48:63]
	ds_read_b128 v[20:23], v83 offset:41536
	ds_read_b128 v[28:31], v83 offset:41568
	s_waitcnt lgkmcnt(1)
	v_mfma_f32_32x32x16_bf16 a[112:127], v[20:23], v[4:7], a[112:127]
	v_mfma_f32_32x32x16_bf16 a[48:63], v[20:23], v[32:35], a[48:63]
	s_waitcnt lgkmcnt(0)
	v_mfma_f32_32x32x16_bf16 a[112:127], v[28:31], v[0:3], a[112:127]
	v_mfma_f32_32x32x16_bf16 a[48:63], v[28:31], v[130:133], a[48:63]
	ds_read_b128 v[20:23], v83 offset:46080
	ds_read_b128 v[28:31], v83 offset:46112
	s_waitcnt lgkmcnt(1)
	v_mfma_f32_32x32x16_bf16 a[64:79], v[20:23], v[12:15], a[80:95]
	v_mfma_f32_32x32x16_bf16 a[80:95], v[20:23], v[24:27], a[96:111]
	ds_read_b128 v[20:23], v83 offset:46144
	s_waitcnt lgkmcnt(1)
	v_mfma_f32_32x32x16_bf16 a[64:79], v[28:31], v[8:11], a[64:79]
	v_mfma_f32_32x32x16_bf16 a[80:95], v[28:31], v[16:19], a[80:95]
	v_add_f32_e32 v28, 0, v52
	v_add_f32_e32 v28, v53, v28
	v_add_f32_e32 v28, v54, v28
	v_add_f32_e32 v28, v55, v28
	v_add_f32_e32 v52, v56, v28
	v_add_f32_e32 v52, v57, v52
	v_add_f32_e32 v52, v58, v52
	v_add_f32_e32 v52, v59, v52
	v_add_f32_e32 v52, v60, v52
	v_add_f32_e32 v52, v61, v52
	v_add_f32_e32 v52, v62, v52
	v_add_f32_e32 v52, v63, v52
	ds_read_b128 v[28:31], v83 offset:46176
	s_waitcnt lgkmcnt(1)
	v_mfma_f32_32x32x16_bf16 a[64:79], v[20:23], v[4:7], a[64:79]
	v_mfma_f32_32x32x16_bf16 a[80:95], v[20:23], v[32:35], a[80:95]
	v_add_f32_e32 v20, v64, v52
	v_add_f32_e32 v20, v65, v20
	v_add_f32_e32 v20, v66, v20
	v_add_f32_e32 v20, v67, v20
	v_add_f32_e32 v20, v36, v20
	v_add_f32_e32 v20, v37, v20
	v_add_f32_e32 v20, v38, v20
	v_add_f32_e32 v20, v39, v20
	v_add_f32_e32 v20, v68, v20
	v_add_f32_e32 v20, v69, v20
	v_add_f32_e32 v20, v70, v20
	v_add_f32_e32 v20, v40, v20
	v_add_f32_e32 v36, v41, v20
	ds_read_b128 v[20:23], v83 offset:50688
	s_waitcnt lgkmcnt(1)
	v_mfma_f32_32x32x16_bf16 a[64:79], v[28:31], v[0:3], a[64:79]
	v_mfma_f32_32x32x16_bf16 a[80:95], v[28:31], v[130:133], a[80:95]
	v_add_f32_e32 v28, v42, v36
	v_add_f32_e32 v28, v43, v28
	v_add_f32_e32 v28, v44, v28
	v_add_f32_e32 v28, v45, v28
	v_add_f32_e32 v28, v46, v28
	v_add_f32_e32 v36, v47, v28
	ds_read_b128 v[28:31], v83 offset:50720
	s_waitcnt lgkmcnt(1)
	v_mfma_f32_32x32x16_bf16 a[96:111], v[20:23], v[12:15], a[32:47]
	v_add_f32_e32 v12, v48, v36
	v_add_f32_e32 v136, v81, v12
	v_add_f32_e32 v12, 0, v49
	v_add_f32_e32 v12, v50, v12
	v_add_f32_e32 v12, v51, v12
	v_add_f32_e32 v12, v71, v12
	v_add_f32_e32 v12, v72, v12
	v_add_f32_e32 v12, v73, v12
	v_add_f32_e32 v12, v74, v12
	v_add_f32_e32 v12, v75, v12
	v_add_f32_e32 v12, v76, v12
	v_add_f32_e32 v12, v77, v12
	v_add_f32_e32 v12, v78, v12
	v_add_f32_e32 v12, v79, v12
	s_waitcnt lgkmcnt(0)
	v_mfma_f32_32x32x16_bf16 a[96:111], v[28:31], v[8:11], a[96:111]
	v_add_f32_e32 v8, v82, v12
	v_add_f32_e32 v8, v84, v8
	v_add_f32_e32 v8, v85, v8
	v_add_f32_e32 v8, v86, v8
	v_add_f32_e32 v8, v87, v8
	v_add_f32_e32 v12, v88, v8
	ds_read_b128 v[8:11], v83 offset:50752
	v_mfma_f32_32x32x16_bf16 a[32:47], v[20:23], v[24:27], a[16:31]
	v_add_f32_e32 v12, v89, v12
	v_add_f32_e32 v12, v90, v12
	v_add_f32_e32 v12, v91, v12
	v_add_f32_e32 v12, v92, v12
	v_add_f32_e32 v12, v93, v12
	v_accvgpr_read_b32 v48, a128
	v_accvgpr_read_b32 v49, a129
	v_mfma_f32_32x32x16_bf16 a[32:47], v[28:31], v[16:19], a[32:47]
	v_add_f32_e32 v16, v94, v12
	ds_read_b128 v[12:15], v83 offset:50784
	v_accvgpr_read_b32 v50, a130
	v_accvgpr_read_b32 v51, a131
	v_accvgpr_read_b32 v52, a132
	v_accvgpr_read_b32 v53, a133
	v_accvgpr_read_b32 v54, a134
	s_waitcnt lgkmcnt(1)
	v_mfma_f32_32x32x16_bf16 a[96:111], v[8:11], v[4:7], a[96:111]
	v_add_f32_e32 v4, v95, v16
	v_add_f32_e32 v4, v96, v4
	v_add_f32_e32 v4, v97, v4
	v_add_f32_e32 v4, v98, v4
	v_add_f32_e32 v4, v99, v4
	v_add_f32_e32 v4, v100, v4
	v_add_f32_e32 v4, v101, v4
	v_add_f32_e32 v4, v102, v4
	v_add_f32_e32 v137, v80, v4
	ds_bpermute_b32 v4, v161, v136
	v_mfma_f32_32x32x16_bf16 a[32:47], v[8:11], v[32:35], a[32:47]
	v_accvgpr_read_b32 v96, a112
	v_accvgpr_read_b32 v32, a48
	v_accvgpr_read_b32 v95, a79
	s_waitcnt lgkmcnt(0)
	v_add_f32_e32 v136, v136, v4
	v_div_scale_f32 v140, s[60:61], v136, v136, 1.0
	v_rcp_f32_e32 v141, v140
	v_mfma_f32_32x32x16_bf16 a[32:47], v[12:15], v[130:133], a[32:47]
	ds_bpermute_b32 v131, v161, v137
	v_accvgpr_read_b32 v16, a80
	v_fma_f32 v130, -v140, v141, 1.0
	v_fmac_f32_e32 v141, v130, v141
	v_div_scale_f32 v130, vcc, 1.0, v136, 1.0
	v_mul_f32_e32 v132, v130, v141
	v_fma_f32 v133, -v140, v132, v130
	s_waitcnt lgkmcnt(0)
	v_add_f32_e32 v131, v137, v131
	v_fmac_f32_e32 v132, v133, v141
	v_div_scale_f32 v133, s[60:61], v131, v131, 1.0
	v_rcp_f32_e32 v137, v133
	v_mfma_f32_32x32x16_bf16 a[96:111], v[12:15], v[0:3], a[96:111]
	v_fma_f32 v130, -v140, v132, v130
	v_div_fmas_f32 v130, v130, v141, v132
	v_div_fixup_f32 v224, v130, v136, 1.0
	v_fma_f32 v130, -v133, v137, 1.0
	v_fmac_f32_e32 v137, v130, v137
	v_div_scale_f32 v130, vcc, 1.0, v131, 1.0
	v_mul_f32_e32 v132, v130, v137
	v_fma_f32 v136, -v133, v132, v130
	v_fmac_f32_e32 v132, v136, v137
	v_fma_f32 v130, -v133, v132, v130
	v_accvgpr_read_b32 v0, a32
	s_nop 0
	v_accvgpr_read_b32 v64, a96
	v_div_fmas_f32 v130, v130, v137, v132
	v_accvgpr_read_b32 v55, a135
	v_accvgpr_read_b32 v56, a136
	v_accvgpr_read_b32 v57, a137
	v_accvgpr_read_b32 v58, a138
	v_accvgpr_read_b32 v59, a139
	v_accvgpr_read_b32 v60, a140
	v_accvgpr_read_b32 v61, a141
	v_accvgpr_read_b32 v62, a142
	v_accvgpr_read_b32 v63, a143
	v_accvgpr_read_b32 v97, a113
	v_accvgpr_read_b32 v98, a114
	v_accvgpr_read_b32 v99, a115
	v_accvgpr_read_b32 v100, a116
	v_accvgpr_read_b32 v101, a117
	v_accvgpr_read_b32 v102, a118
	v_accvgpr_read_b32 v103, a119
	v_accvgpr_read_b32 v104, a120
	v_accvgpr_read_b32 v105, a121
	v_accvgpr_read_b32 v106, a122
	v_accvgpr_read_b32 v107, a123
	v_accvgpr_read_b32 v108, a124
	v_accvgpr_read_b32 v109, a125
	v_accvgpr_read_b32 v110, a126
	v_accvgpr_read_b32 v111, a127
	v_accvgpr_read_b32 v33, a49
	v_accvgpr_read_b32 v34, a50
	v_accvgpr_read_b32 v35, a51
	v_accvgpr_read_b32 v36, a52
	v_accvgpr_read_b32 v37, a53
	v_accvgpr_read_b32 v38, a54
	v_accvgpr_read_b32 v39, a55
	v_accvgpr_read_b32 v40, a56
	v_accvgpr_read_b32 v41, a57
	v_accvgpr_read_b32 v42, a58
	v_accvgpr_read_b32 v43, a59
	v_accvgpr_read_b32 v44, a60
	v_accvgpr_read_b32 v45, a61
	v_accvgpr_read_b32 v46, a62
	v_accvgpr_read_b32 v47, a63
	v_accvgpr_read_b32 v94, a78
	v_accvgpr_read_b32 v93, a77
	v_accvgpr_read_b32 v92, a76
	v_accvgpr_read_b32 v91, a75
	v_accvgpr_read_b32 v90, a74
	v_accvgpr_read_b32 v89, a73
	v_accvgpr_read_b32 v88, a72
	v_accvgpr_read_b32 v87, a71
	v_accvgpr_read_b32 v86, a70
	v_accvgpr_read_b32 v85, a69
	v_accvgpr_read_b32 v84, a68
	v_accvgpr_read_b32 v83, a67
	v_accvgpr_read_b32 v82, a66
	v_accvgpr_read_b32 v81, a65
	v_accvgpr_read_b32 v80, a64
	v_accvgpr_read_b32 v17, a81
	v_accvgpr_read_b32 v18, a82
	v_accvgpr_read_b32 v19, a83
	v_accvgpr_read_b32 v20, a84
	v_accvgpr_read_b32 v21, a85
	v_accvgpr_read_b32 v22, a86
	v_accvgpr_read_b32 v23, a87
	v_accvgpr_read_b32 v24, a88
	v_accvgpr_read_b32 v25, a89
	v_accvgpr_read_b32 v26, a90
	v_accvgpr_read_b32 v27, a91
	v_accvgpr_read_b32 v28, a92
	v_accvgpr_read_b32 v29, a93
	v_accvgpr_read_b32 v30, a94
	v_accvgpr_read_b32 v31, a95
	v_accvgpr_read_b32 v65, a97
	v_accvgpr_read_b32 v66, a98
	v_accvgpr_read_b32 v67, a99
	v_accvgpr_read_b32 v68, a100
	v_accvgpr_read_b32 v69, a101
	v_accvgpr_read_b32 v70, a102
	v_accvgpr_read_b32 v71, a103
	v_accvgpr_read_b32 v72, a104
	v_accvgpr_read_b32 v73, a105
	v_accvgpr_read_b32 v74, a106
	v_accvgpr_read_b32 v75, a107
	v_accvgpr_read_b32 v76, a108
	v_accvgpr_read_b32 v77, a109
	v_accvgpr_read_b32 v78, a110
	v_accvgpr_read_b32 v79, a111
	v_accvgpr_read_b32 v1, a33
	v_accvgpr_read_b32 v2, a34
	v_accvgpr_read_b32 v3, a35
	v_accvgpr_read_b32 v4, a36
	v_accvgpr_read_b32 v5, a37
	v_accvgpr_read_b32 v6, a38
	v_accvgpr_read_b32 v7, a39
	v_accvgpr_read_b32 v8, a40
	v_accvgpr_read_b32 v9, a41
	v_accvgpr_read_b32 v10, a42
	v_accvgpr_read_b32 v11, a43
	v_accvgpr_read_b32 v12, a44
	v_accvgpr_read_b32 v13, a45
	v_accvgpr_read_b32 v14, a46
	v_accvgpr_read_b32 v15, a47
	v_div_fixup_f32 v172, v130, v131, 1.0
	s_barrier
	s_and_saveexec_b64 s[60:61], s[4:5]
	s_cbranch_execz .LBB0_1090
	v_accvgpr_read_b32 v133, a252
	v_mul_f32_e32 v130, v133, v224
	v_mul_f32_e32 v131, v112, v130
	v_mul_f32_e32 v132, v113, v130
	ds_write2st64_b32 v139, v131, v132 offset1:1
	v_mul_f32_e32 v131, v114, v130
	v_mul_f32_e32 v132, v115, v130
	ds_write2st64_b32 v139, v131, v132 offset0:2 offset1:3
	v_mul_f32_e32 v131, v116, v130
	v_mul_f32_e32 v132, v117, v130
	ds_write2st64_b32 v139, v131, v132 offset0:4 offset1:5
	v_mul_f32_e32 v131, v118, v130
	v_mul_f32_e32 v132, v119, v130
	ds_write2st64_b32 v139, v131, v132 offset0:6 offset1:7
	v_mul_f32_e32 v131, v120, v130
	v_mul_f32_e32 v132, v121, v130
	ds_write2st64_b32 v139, v131, v132 offset0:8 offset1:9
	v_mul_f32_e32 v131, v122, v130
	v_mul_f32_e32 v132, v123, v130
	ds_write2st64_b32 v139, v131, v132 offset0:10 offset1:11
	v_mul_f32_e32 v131, v124, v130
	v_mul_f32_e32 v132, v125, v130
	ds_write2st64_b32 v139, v131, v132 offset0:12 offset1:13
	v_mul_f32_e32 v131, v126, v130
	v_mul_f32_e32 v132, v127, v130
	ds_write2st64_b32 v139, v131, v132 offset0:14 offset1:15
	v_mul_f32_e32 v131, v96, v130
	v_mul_f32_e32 v132, v97, v130
	ds_write2st64_b32 v139, v131, v132 offset0:16 offset1:17
	v_mul_f32_e32 v131, v98, v130
	v_mul_f32_e32 v132, v99, v130
	ds_write2st64_b32 v139, v131, v132 offset0:18 offset1:19
	v_mul_f32_e32 v131, v100, v130
	v_mul_f32_e32 v132, v101, v130
	ds_write2st64_b32 v139, v131, v132 offset0:20 offset1:21
	v_mul_f32_e32 v131, v102, v130
	v_mul_f32_e32 v132, v103, v130
	ds_write2st64_b32 v139, v131, v132 offset0:22 offset1:23
	v_mul_f32_e32 v131, v104, v130
	v_mul_f32_e32 v132, v105, v130
	ds_write2st64_b32 v139, v131, v132 offset0:24 offset1:25
	v_mul_f32_e32 v131, v106, v130
	v_mul_f32_e32 v132, v107, v130
	ds_write2st64_b32 v139, v131, v132 offset0:26 offset1:27
	v_mul_f32_e32 v131, v108, v130
	v_mul_f32_e32 v132, v109, v130
	ds_write2st64_b32 v139, v131, v132 offset0:28 offset1:29
	v_mul_f32_e32 v131, v110, v130
	v_mul_f32_e32 v132, v111, v130
	ds_write2st64_b32 v139, v131, v132 offset0:30 offset1:31
	v_mul_f32_e32 v131, v80, v130
	v_mul_f32_e32 v132, v81, v130
	ds_write2st64_b32 v139, v131, v132 offset0:32 offset1:33
	v_mul_f32_e32 v131, v82, v130
	v_mul_f32_e32 v132, v83, v130
	ds_write2st64_b32 v139, v131, v132 offset0:34 offset1:35
	v_mul_f32_e32 v131, v84, v130
	v_mul_f32_e32 v132, v85, v130
	ds_write2st64_b32 v139, v131, v132 offset0:36 offset1:37
	v_mul_f32_e32 v131, v86, v130
	v_mul_f32_e32 v132, v87, v130
	ds_write2st64_b32 v139, v131, v132 offset0:38 offset1:39
	v_mul_f32_e32 v131, v88, v130
	v_mul_f32_e32 v132, v89, v130
	ds_write2st64_b32 v139, v131, v132 offset0:40 offset1:41
	v_mul_f32_e32 v131, v90, v130
	v_mul_f32_e32 v132, v91, v130
	ds_write2st64_b32 v139, v131, v132 offset0:42 offset1:43
	v_mul_f32_e32 v131, v92, v130
	v_mul_f32_e32 v132, v93, v130
	ds_write2st64_b32 v139, v131, v132 offset0:44 offset1:45
	v_mul_f32_e32 v131, v94, v130
	v_mul_f32_e32 v132, v95, v130
	ds_write2st64_b32 v139, v131, v132 offset0:46 offset1:47
	v_mul_f32_e32 v131, v64, v130
	v_mul_f32_e32 v132, v65, v130
	ds_write2st64_b32 v139, v131, v132 offset0:48 offset1:49
	v_mul_f32_e32 v131, v66, v130
	v_mul_f32_e32 v132, v67, v130
	ds_write2st64_b32 v139, v131, v132 offset0:50 offset1:51
	v_mul_f32_e32 v131, v68, v130
	v_mul_f32_e32 v132, v69, v130
	ds_write2st64_b32 v139, v131, v132 offset0:52 offset1:53
	v_mul_f32_e32 v131, v70, v130
	v_mul_f32_e32 v132, v71, v130
	ds_write2st64_b32 v139, v131, v132 offset0:54 offset1:55
	v_mul_f32_e32 v131, v72, v130
	v_mul_f32_e32 v132, v73, v130
	ds_write2st64_b32 v139, v131, v132 offset0:56 offset1:57
	v_mul_f32_e32 v131, v74, v130
	v_mul_f32_e32 v132, v75, v130
	ds_write2st64_b32 v139, v131, v132 offset0:58 offset1:59
	v_mul_f32_e32 v131, v76, v130
	v_mul_f32_e32 v132, v77, v130
	ds_write2st64_b32 v139, v131, v132 offset0:60 offset1:61
	v_mul_f32_e32 v131, v78, v130
	v_mul_f32_e32 v130, v79, v130
	ds_write2st64_b32 v139, v131, v130 offset0:62 offset1:63
	v_mul_f32_e32 v130, v133, v172
	v_mul_f32_e32 v131, v48, v130
	v_mul_f32_e32 v132, v49, v130
	ds_write2st64_b32 v254, v131, v132 offset1:1
	v_mul_f32_e32 v131, v50, v130
	v_mul_f32_e32 v132, v51, v130
	ds_write2st64_b32 v254, v131, v132 offset0:2 offset1:3
	v_mul_f32_e32 v131, v52, v130
	v_mul_f32_e32 v132, v53, v130
	ds_write2st64_b32 v254, v131, v132 offset0:4 offset1:5
	v_mul_f32_e32 v131, v54, v130
	v_mul_f32_e32 v132, v55, v130
	ds_write2st64_b32 v254, v131, v132 offset0:6 offset1:7
	v_mul_f32_e32 v131, v56, v130
	v_mul_f32_e32 v132, v57, v130
	ds_write2st64_b32 v254, v131, v132 offset0:8 offset1:9
	v_mul_f32_e32 v131, v58, v130
	v_mul_f32_e32 v132, v59, v130
	ds_write2st64_b32 v254, v131, v132 offset0:10 offset1:11
	v_mul_f32_e32 v131, v60, v130
	v_mul_f32_e32 v132, v61, v130
	ds_write2st64_b32 v254, v131, v132 offset0:12 offset1:13
	v_mul_f32_e32 v131, v62, v130
	v_mul_f32_e32 v132, v63, v130
	ds_write2st64_b32 v254, v131, v132 offset0:14 offset1:15
	v_mul_f32_e32 v131, v32, v130
	v_mul_f32_e32 v132, v33, v130
	ds_write2st64_b32 v254, v131, v132 offset0:16 offset1:17
	v_mul_f32_e32 v131, v34, v130
	v_mul_f32_e32 v132, v35, v130
	ds_write2st64_b32 v254, v131, v132 offset0:18 offset1:19
	v_mul_f32_e32 v131, v36, v130
	v_mul_f32_e32 v132, v37, v130
	ds_write2st64_b32 v254, v131, v132 offset0:20 offset1:21
	v_mul_f32_e32 v131, v38, v130
	v_mul_f32_e32 v132, v39, v130
	ds_write2st64_b32 v254, v131, v132 offset0:22 offset1:23
	v_mul_f32_e32 v131, v40, v130
	v_mul_f32_e32 v132, v41, v130
	ds_write2st64_b32 v254, v131, v132 offset0:24 offset1:25
	v_mul_f32_e32 v131, v42, v130
	v_mul_f32_e32 v132, v43, v130
	ds_write2st64_b32 v254, v131, v132 offset0:26 offset1:27
	v_mul_f32_e32 v131, v44, v130
	v_mul_f32_e32 v132, v45, v130
	ds_write2st64_b32 v254, v131, v132 offset0:28 offset1:29
	v_mul_f32_e32 v131, v46, v130
	v_mul_f32_e32 v132, v47, v130
	ds_write2st64_b32 v254, v131, v132 offset0:30 offset1:31
	v_mul_f32_e32 v131, v16, v130
	v_mul_f32_e32 v132, v17, v130
	ds_write2st64_b32 v254, v131, v132 offset0:32 offset1:33
	v_mul_f32_e32 v131, v18, v130
	v_mul_f32_e32 v132, v19, v130
	ds_write2st64_b32 v254, v131, v132 offset0:34 offset1:35
	v_mul_f32_e32 v131, v20, v130
	v_mul_f32_e32 v132, v21, v130
	ds_write2st64_b32 v254, v131, v132 offset0:36 offset1:37
	v_mul_f32_e32 v131, v22, v130
	v_mul_f32_e32 v132, v23, v130
	ds_write2st64_b32 v254, v131, v132 offset0:38 offset1:39
	v_mul_f32_e32 v131, v24, v130
	v_mul_f32_e32 v132, v25, v130
	ds_write2st64_b32 v254, v131, v132 offset0:40 offset1:41
	v_mul_f32_e32 v131, v26, v130
	v_mul_f32_e32 v132, v27, v130
	ds_write2st64_b32 v254, v131, v132 offset0:42 offset1:43
	v_mul_f32_e32 v131, v28, v130
	v_mul_f32_e32 v132, v29, v130
	ds_write2st64_b32 v254, v131, v132 offset0:44 offset1:45
	v_mul_f32_e32 v131, v30, v130
	v_mul_f32_e32 v132, v31, v130
	ds_write2st64_b32 v254, v131, v132 offset0:46 offset1:47
	v_mul_f32_e32 v131, v0, v130
	v_mul_f32_e32 v132, v1, v130
	ds_write2st64_b32 v254, v131, v132 offset0:48 offset1:49
	v_mul_f32_e32 v131, v2, v130
	v_mul_f32_e32 v132, v3, v130
	ds_write2st64_b32 v254, v131, v132 offset0:50 offset1:51
	v_mul_f32_e32 v131, v4, v130
	v_mul_f32_e32 v132, v5, v130
	ds_write2st64_b32 v254, v131, v132 offset0:52 offset1:53
	v_mul_f32_e32 v131, v6, v130
	v_mul_f32_e32 v132, v7, v130
	ds_write2st64_b32 v254, v131, v132 offset0:54 offset1:55
	v_mul_f32_e32 v131, v8, v130
	v_mul_f32_e32 v132, v9, v130
	ds_write2st64_b32 v254, v131, v132 offset0:56 offset1:57
	v_mul_f32_e32 v131, v10, v130
	v_mul_f32_e32 v132, v11, v130
	ds_write2st64_b32 v254, v131, v132 offset0:58 offset1:59
	v_mul_f32_e32 v131, v12, v130
	v_mul_f32_e32 v132, v13, v130
	ds_write2st64_b32 v254, v131, v132 offset0:60 offset1:61
	v_mul_f32_e32 v131, v14, v130
	v_mul_f32_e32 v130, v15, v130
	ds_write2st64_b32 v254, v131, v130 offset0:62 offset1:63

.LBB0_2271:
	s_and_b32 s61, s60, 1
	s_xor_b32 s62, s61, 1
	s_mulk_i32 s61, 0x4800
	s_mulk_i32 s62, 0x4800
	v_add_u32_e32 v233, s61, v128
	v_add_u32_e32 v234, s62, v150
	s_waitcnt vmcnt(0) lgkmcnt(0)
	s_barrier
	ds_read_b128 a[144:147], v233
	ds_read_b128 a[148:151], v233 offset:32
	ds_read_b128 a[152:155], v233 offset:64
	ds_read_b128 a[156:159], v233 offset:96
	s_waitcnt lgkmcnt(3)
	v_mfma_f32_32x32x16_bf16 v[184:199], a[144:147], v[28:31], v[32:47]
	s_cmp_eq_u32 s60, 0
	s_cselect_b32 s32, 0x9000, s61
	v_add3_u32 v220, s32, v151, v134
	v_add3_u32 v221, s32, v156, v134
	v_add3_u32 v222, s32, v157, v134
	v_mfma_f32_32x32x16_bf16 v[168:183], a[144:147], v[12:15], v[32:47]
	v_add3_u32 v232, s32, v158, v134
	ds_write_b128 v220, v[140:143] offset:36864
	ds_write_b128 v221, v[216:219] offset:36864
	ds_write_b128 v222, v[224:227] offset:36864
	ds_read_b128 a[144:147], v233 offset:4608
	s_waitcnt lgkmcnt(6)
	v_mfma_f32_32x32x16_bf16 v[184:199], a[148:151], v[24:27], v[184:199]
	ds_write_b128 v232, v[228:231] offset:36864
	v_lshl_add_u64 v[98:99], v[82:83], 0, v[154:155]
	global_load_dwordx4 v[64:67], v[98:99], off
	v_lshl_add_u64 v[98:99], v[84:85], 0, v[154:155]
	v_mfma_f32_32x32x16_bf16 v[168:183], a[148:151], v[8:11], v[168:183]
	global_load_dwordx4 v[68:71], v[98:99], off
	v_lshl_add_u64 v[98:99], v[86:87], 0, v[154:155]
	global_load_dwordx4 v[72:75], v[98:99], off
	v_lshl_add_u64 v[98:99], v[88:89], 0, v[154:155]
	ds_read_b128 a[148:151], v233 offset:4640
	s_waitcnt lgkmcnt(7)
	v_mfma_f32_32x32x16_bf16 v[184:199], a[152:155], v[20:23], v[184:199]
	global_load_dwordx4 v[76:79], v[98:99], off
	v_lshl_add_u64 v[98:99], v[90:91], 0, v[154:155]
	global_load_dwordx4 v[140:143], v[98:99], off
	v_lshl_add_u64 v[98:99], v[92:93], 0, v[154:155]
	v_mfma_f32_32x32x16_bf16 v[168:183], a[152:155], v[4:7], v[168:183]
	global_load_dwordx4 v[216:219], v[98:99], off
	v_lshl_add_u64 v[98:99], v[94:95], 0, v[154:155]
	global_load_dwordx4 v[224:227], v[98:99], off
	v_lshl_add_u64 v[98:99], v[96:97], 0, v[154:155]
	ds_read_b128 a[152:155], v233 offset:4672
	s_waitcnt lgkmcnt(7)
	v_mfma_f32_32x32x16_bf16 v[184:199], a[156:159], v[16:19], v[184:199]
	global_load_dwordx4 v[228:231], v[98:99], off
	v_lshl_add_u64 v[90:91], v[90:91], 0, s[56:57]
	v_lshl_add_u64 v[92:93], v[92:93], 0, s[56:57]
	v_lshl_add_u64 v[94:95], v[94:95], 0, s[56:57]
	v_mfma_f32_32x32x16_bf16 v[168:183], a[156:159], v[0:3], v[168:183]
	v_lshl_add_u64 v[96:97], v[96:97], 0, s[56:57]
	v_accvgpr_write_b32 a160, v48
	v_accvgpr_write_b32 a161, v49
	v_accvgpr_write_b32 a162, v50
	ds_read_b128 a[156:159], v233 offset:4704
	s_waitcnt lgkmcnt(4)
	v_mfma_f32_32x32x16_bf16 v[200:215], a[144:147], v[28:31], v[32:47]
	v_accvgpr_write_b32 a163, v51
	v_accvgpr_write_b32 a164, v52
	v_accvgpr_write_b32 a165, v53
	v_accvgpr_write_b32 a166, v54
	v_accvgpr_write_b32 a167, v55
	v_mfma_f32_32x32x16_bf16 v[100:115], a[144:147], v[12:15], v[32:47]
	v_accvgpr_write_b32 a168, v56
	v_accvgpr_write_b32 a169, v57
	v_accvgpr_write_b32 a170, v58
	v_accvgpr_write_b32 a171, v59
	s_waitcnt lgkmcnt(2)
	v_mfma_f32_32x32x16_bf16 v[200:215], a[148:151], v[24:27], v[200:215]
	v_accvgpr_write_b32 a172, v60
	v_accvgpr_write_b32 a173, v61
	v_accvgpr_write_b32 a174, v62
	v_accvgpr_write_b32 a175, v63
	v_mfma_f32_32x32x16_bf16 v[100:115], a[148:151], v[8:11], v[100:115]
	v_accvgpr_write_b32 a176, v116
	v_accvgpr_write_b32 a177, v117
	v_accvgpr_write_b32 a178, v118
	v_accvgpr_write_b32 a179, v119
	s_waitcnt lgkmcnt(1)
	v_mfma_f32_32x32x16_bf16 v[200:215], a[152:155], v[20:23], v[200:215]
	v_accvgpr_write_b32 a180, v120
	v_accvgpr_write_b32 a181, v121
	v_accvgpr_write_b32 a182, v122
	v_accvgpr_write_b32 a183, v123
	v_mfma_f32_32x32x16_bf16 v[100:115], a[152:155], v[4:7], v[100:115]
	v_accvgpr_write_b32 a184, v124
	v_accvgpr_write_b32 a185, v125
	v_accvgpr_write_b32 a186, v126
	v_accvgpr_write_b32 a187, v127
	s_waitcnt lgkmcnt(0)
	v_mfma_f32_32x32x16_bf16 v[200:215], a[156:159], v[16:19], v[200:215]
	v_accvgpr_write_b32 a188, v130
	v_accvgpr_write_b32 a189, v131
	v_accvgpr_write_b32 a190, v132
	v_accvgpr_write_b32 a191, v133
	v_mfma_f32_32x32x16_bf16 v[100:115], a[156:159], v[0:3], v[100:115]
	v_lshl_add_u64 v[82:83], v[82:83], 0, s[54:55]
	v_lshl_add_u64 v[84:85], v[84:85], 0, s[54:55]
	v_lshl_add_u64 v[86:87], v[86:87], 0, s[54:55]
	v_lshl_add_u64 v[88:89], v[88:89], 0, s[54:55]
	ds_read_b128 a[144:147], v234 offset:36864
	ds_read_b128 a[148:151], v234 offset:36896
	ds_read_b128 a[152:155], v234 offset:36928
	ds_read_b128 a[156:159], v234 offset:36960
	s_waitcnt lgkmcnt(3)
	v_mfma_f32_32x32x16_bf16 a[128:143], a[144:147], a[160:163], a[128:143]
	v_exp_f32_e32 v184, v184
	v_exp_f32_e32 v185, v185
	v_exp_f32_e32 v186, v186
	v_mfma_f32_32x32x16_bf16 a[112:127], a[144:147], a[176:179], a[112:127]
	v_exp_f32_e32 v187, v187
	v_exp_f32_e32 v188, v188
	v_exp_f32_e32 v189, v189
	v_exp_f32_e32 v190, v190
	ds_read_b128 a[144:147], v234 offset:41472
	s_waitcnt lgkmcnt(3)
	v_mfma_f32_32x32x16_bf16 a[128:143], a[148:151], a[164:167], a[128:143]
	v_exp_f32_e32 v191, v191
	v_exp_f32_e32 v192, v192
	v_exp_f32_e32 v193, v193
	v_mfma_f32_32x32x16_bf16 a[112:127], a[148:151], a[180:183], a[112:127]
	v_exp_f32_e32 v194, v194
	v_exp_f32_e32 v195, v195
	v_exp_f32_e32 v196, v196
	v_exp_f32_e32 v197, v197
	ds_read_b128 a[148:151], v234 offset:41504
	s_waitcnt lgkmcnt(3)
	v_mfma_f32_32x32x16_bf16 a[128:143], a[152:155], a[168:171], a[128:143]
	v_exp_f32_e32 v198, v198
	v_exp_f32_e32 v199, v199
	v_pk_add_f32 v[136:137], v[184:185], v[186:187]
	v_pk_add_f32 v[136:137], v[136:137], v[188:189]
	v_mfma_f32_32x32x16_bf16 a[112:127], a[152:155], a[184:187], a[112:127]
	v_pk_add_f32 v[136:137], v[136:137], v[190:191]
	v_pk_add_f32 v[136:137], v[136:137], v[192:193]
	v_pk_add_f32 v[136:137], v[136:137], v[194:195]
	ds_read_b128 a[152:155], v234 offset:41536
	s_waitcnt lgkmcnt(3)
	v_mfma_f32_32x32x16_bf16 a[128:143], a[156:159], a[172:175], a[128:143]
	v_pk_add_f32 v[136:137], v[136:137], v[196:197]
	v_pk_add_f32 v[136:137], v[136:137], v[198:199]
	v_cvt_pk_bf16_f32 v48, v184, v185
	v_cvt_pk_bf16_f32 v49, v186, v187
	v_cvt_pk_bf16_f32 v50, v188, v189
	v_cvt_pk_bf16_f32 v51, v190, v191
	v_cvt_pk_bf16_f32 v52, v192, v193
	v_mfma_f32_32x32x16_bf16 a[112:127], a[156:159], a[188:191], a[112:127]
	v_cvt_pk_bf16_f32 v53, v194, v195
	v_cvt_pk_bf16_f32 v54, v196, v197
	v_cvt_pk_bf16_f32 v55, v198, v199
	v_add3_u32 v220, s62, v151, v134
	v_add3_u32 v221, s62, v156, v134
	s_waitcnt vmcnt(7)
	ds_write_b128 v220, v[64:67]
	s_waitcnt vmcnt(6)
	ds_read_b128 a[156:159], v234 offset:41568
	s_waitcnt lgkmcnt(4)
	v_mfma_f32_32x32x16_bf16 a[48:63], a[144:147], a[160:163], a[48:63]
	ds_write_b128 v221, v[68:71]
	s_waitcnt vmcnt(5)
	ds_write_b128 v220, v[72:75] offset:9216
	s_waitcnt vmcnt(4)
	ds_write_b128 v221, v[76:79] offset:9216
	v_mfma_f32_32x32x16_bf16 a[64:79], a[144:147], a[176:179], a[64:79]
	v_exp_f32_e32 v168, v168
	v_exp_f32_e32 v169, v169
	v_exp_f32_e32 v170, v170
	v_exp_f32_e32 v171, v171
	ds_read_b128 a[144:147], v234 offset:46080
	s_waitcnt lgkmcnt(7)
	v_mfma_f32_32x32x16_bf16 a[48:63], a[148:151], a[164:167], a[48:63]
	v_exp_f32_e32 v172, v172
	v_exp_f32_e32 v173, v173
	v_exp_f32_e32 v174, v174
	v_exp_f32_e32 v175, v175
	v_mfma_f32_32x32x16_bf16 a[64:79], a[148:151], a[180:183], a[64:79]
	v_exp_f32_e32 v176, v176
	v_exp_f32_e32 v177, v177
	v_exp_f32_e32 v178, v178
	ds_read_b128 a[148:151], v234 offset:46112
	s_waitcnt lgkmcnt(7)
	v_mfma_f32_32x32x16_bf16 a[48:63], a[152:155], a[168:171], a[48:63]
	v_exp_f32_e32 v179, v179
	v_exp_f32_e32 v180, v180
	v_exp_f32_e32 v181, v181
	v_exp_f32_e32 v182, v182
	v_mfma_f32_32x32x16_bf16 a[64:79], a[152:155], a[184:187], a[64:79]
	v_exp_f32_e32 v183, v183
	v_pk_add_f32 v[144:145], v[168:169], v[170:171]
	v_pk_add_f32 v[144:145], v[144:145], v[172:173]
	v_pk_add_f32 v[144:145], v[144:145], v[174:175]
	ds_read_b128 a[152:155], v234 offset:46144
	s_waitcnt lgkmcnt(6)
	v_mfma_f32_32x32x16_bf16 a[48:63], a[156:159], a[172:175], a[48:63]
	v_pk_add_f32 v[144:145], v[144:145], v[176:177]
	v_pk_add_f32 v[144:145], v[144:145], v[178:179]
	v_pk_add_f32 v[144:145], v[144:145], v[180:181]
	v_mfma_f32_32x32x16_bf16 a[64:79], a[156:159], a[188:191], a[64:79]
	v_pk_add_f32 v[144:145], v[144:145], v[182:183]
	v_cvt_pk_bf16_f32 v116, v168, v169
	v_cvt_pk_bf16_f32 v117, v170, v171
	v_cvt_pk_bf16_f32 v118, v172, v173
	v_cvt_pk_bf16_f32 v119, v174, v175
	v_cvt_pk_bf16_f32 v120, v176, v177
	v_cvt_pk_bf16_f32 v121, v178, v179
	v_cvt_pk_bf16_f32 v122, v180, v181
	ds_read_b128 a[156:159], v234 offset:46176
	s_waitcnt lgkmcnt(3)
	v_mfma_f32_32x32x16_bf16 a[80:95], a[144:147], a[160:163], a[80:95]
	v_cvt_pk_bf16_f32 v123, v182, v183
	v_exp_f32_e32 v200, v200
	v_exp_f32_e32 v201, v201
	v_exp_f32_e32 v202, v202
	v_mfma_f32_32x32x16_bf16 a[96:111], a[144:147], a[176:179], a[96:111]
	v_exp_f32_e32 v203, v203
	v_exp_f32_e32 v204, v204
	v_exp_f32_e32 v205, v205
	ds_read_b128 a[144:147], v234 offset:50688
	s_waitcnt lgkmcnt(3)
	v_mfma_f32_32x32x16_bf16 a[80:95], a[148:151], a[164:167], a[80:95]
	v_exp_f32_e32 v206, v206
	v_exp_f32_e32 v207, v207
	v_exp_f32_e32 v208, v208
	v_exp_f32_e32 v209, v209
	v_mfma_f32_32x32x16_bf16 a[96:111], a[148:151], a[180:183], a[96:111]
	v_exp_f32_e32 v210, v210
	v_exp_f32_e32 v211, v211
	v_exp_f32_e32 v212, v212
	v_exp_f32_e32 v213, v213
	ds_read_b128 a[148:151], v234 offset:50720
	s_waitcnt lgkmcnt(3)
	v_mfma_f32_32x32x16_bf16 a[80:95], a[152:155], a[168:171], a[80:95]
	v_exp_f32_e32 v214, v214
	v_exp_f32_e32 v215, v215
	v_pk_add_f32 v[136:137], v[136:137], v[200:201]
	v_mfma_f32_32x32x16_bf16 a[96:111], a[152:155], a[184:187], a[96:111]
	v_pk_add_f32 v[136:137], v[136:137], v[202:203]
	v_pk_add_f32 v[136:137], v[136:137], v[204:205]
	v_pk_add_f32 v[136:137], v[136:137], v[206:207]
	v_pk_add_f32 v[136:137], v[136:137], v[208:209]
	ds_read_b128 a[152:155], v234 offset:50752
	s_waitcnt lgkmcnt(3)
	v_mfma_f32_32x32x16_bf16 a[80:95], a[156:159], a[172:175], a[80:95]
	v_pk_add_f32 v[136:137], v[136:137], v[210:211]
	v_pk_add_f32 v[136:137], v[136:137], v[212:213]
	v_pk_add_f32 v[136:137], v[136:137], v[214:215]
	v_cvt_pk_bf16_f32 v56, v200, v201
	v_cvt_pk_bf16_f32 v57, v202, v203
	v_mfma_f32_32x32x16_bf16 a[96:111], a[156:159], a[188:191], a[96:111]
	v_cvt_pk_bf16_f32 v58, v204, v205
	v_cvt_pk_bf16_f32 v59, v206, v207
	v_cvt_pk_bf16_f32 v60, v208, v209
	v_cvt_pk_bf16_f32 v61, v210, v211
	v_cvt_pk_bf16_f32 v62, v212, v213
	v_cvt_pk_bf16_f32 v63, v214, v215
	v_add_f32_e32 v235, v136, v137
	ds_read_b128 a[156:159], v234 offset:50784
	s_waitcnt lgkmcnt(3)
	v_mfma_f32_32x32x16_bf16 a[32:47], a[144:147], a[160:163], a[32:47]
	v_add_f32_e32 v81, v81, v235
	v_exp_f32_e32 v100, v100
	v_exp_f32_e32 v101, v101
	v_exp_f32_e32 v102, v102
	v_mfma_f32_32x32x16_bf16 a[16:31], a[144:147], a[176:179], a[16:31]
	v_exp_f32_e32 v103, v103
	v_exp_f32_e32 v104, v104
	v_exp_f32_e32 v105, v105
	v_exp_f32_e32 v106, v106
	s_waitcnt lgkmcnt(2)
	v_mfma_f32_32x32x16_bf16 a[32:47], a[148:151], a[164:167], a[32:47]
	v_exp_f32_e32 v107, v107
	v_exp_f32_e32 v108, v108
	v_exp_f32_e32 v109, v109
	v_mfma_f32_32x32x16_bf16 a[16:31], a[148:151], a[180:183], a[16:31]
	v_exp_f32_e32 v110, v110
	v_exp_f32_e32 v111, v111
	v_exp_f32_e32 v112, v112
	v_exp_f32_e32 v113, v113
	s_waitcnt lgkmcnt(1)
	v_mfma_f32_32x32x16_bf16 a[32:47], a[152:155], a[168:171], a[32:47]
	v_exp_f32_e32 v114, v114
	v_exp_f32_e32 v115, v115
	v_pk_add_f32 v[144:145], v[144:145], v[100:101]
	v_pk_add_f32 v[144:145], v[144:145], v[102:103]
	v_mfma_f32_32x32x16_bf16 a[16:31], a[152:155], a[184:187], a[16:31]
	v_pk_add_f32 v[144:145], v[144:145], v[104:105]
	v_pk_add_f32 v[144:145], v[144:145], v[106:107]
	v_pk_add_f32 v[144:145], v[144:145], v[108:109]
	s_waitcnt lgkmcnt(0)
	v_mfma_f32_32x32x16_bf16 a[32:47], a[156:159], a[172:175], a[32:47]
	v_pk_add_f32 v[144:145], v[144:145], v[110:111]
	v_pk_add_f32 v[144:145], v[144:145], v[112:113]
	v_pk_add_f32 v[144:145], v[144:145], v[114:115]
	v_cvt_pk_bf16_f32 v124, v100, v101
	v_cvt_pk_bf16_f32 v125, v102, v103
	v_mfma_f32_32x32x16_bf16 a[16:31], a[156:159], a[188:191], a[16:31]
	v_cvt_pk_bf16_f32 v126, v104, v105
	v_cvt_pk_bf16_f32 v127, v106, v107
	v_cvt_pk_bf16_f32 v130, v108, v109
	v_cvt_pk_bf16_f32 v131, v110, v111
	v_cvt_pk_bf16_f32 v132, v112, v113
	v_cvt_pk_bf16_f32 v133, v114, v115
	v_add_f32_e32 v235, v144, v145
	v_add_f32_e32 v80, v80, v235
	s_add_i32 s60, s60, 1
	s_cmp_eq_u32 s4, s60
	s_cbranch_scc0 .LBB0_2271
	s_waitcnt vmcnt(0) lgkmcnt(0)
	s_barrier
	v_add3_u32 v220, s62, v151, v134
	v_add3_u32 v221, s62, v156, v134
	v_add3_u32 v222, s62, v157, v134
	v_add3_u32 v232, s62, v158, v134
	ds_write_b128 v220, v[140:143] offset:36864
	ds_write_b128 v221, v[216:219] offset:36864
	ds_write_b128 v222, v[224:227] offset:36864
	ds_write_b128 v232, v[228:231] offset:36864
	v_add_u32_e32 v234, s61, v150
	ds_read_b128 a[144:147], v234 offset:36864
	ds_read_b128 a[148:151], v234 offset:36896
	ds_read_b128 a[152:155], v234 offset:36928
	ds_read_b128 a[156:159], v234 offset:36960
	s_waitcnt lgkmcnt(3)
	v_mfma_f32_32x32x16_bf16 a[128:143], a[144:147], v[48:51], a[128:143]
	v_mfma_f32_32x32x16_bf16 a[112:127], a[144:147], v[116:119], a[112:127]
	ds_read_b128 a[144:147], v234 offset:41472
	s_waitcnt lgkmcnt(3)
	v_mfma_f32_32x32x16_bf16 a[128:143], a[148:151], v[52:55], a[128:143]
	v_mfma_f32_32x32x16_bf16 a[112:127], a[148:151], v[120:123], a[112:127]
	ds_read_b128 a[148:151], v234 offset:41504
	s_waitcnt lgkmcnt(3)
	v_mfma_f32_32x32x16_bf16 a[128:143], a[152:155], v[56:59], a[128:143]
	v_mfma_f32_32x32x16_bf16 a[112:127], a[152:155], v[124:127], a[112:127]
	ds_read_b128 a[152:155], v234 offset:41536
	s_waitcnt lgkmcnt(3)
	v_mfma_f32_32x32x16_bf16 a[128:143], a[156:159], v[60:63], a[128:143]
	v_mfma_f32_32x32x16_bf16 a[112:127], a[156:159], v[130:133], a[112:127]
	ds_read_b128 a[156:159], v234 offset:41568
	s_waitcnt lgkmcnt(3)
	v_mfma_f32_32x32x16_bf16 a[48:63], a[144:147], v[48:51], a[48:63]
	v_mfma_f32_32x32x16_bf16 a[64:79], a[144:147], v[116:119], a[64:79]
	ds_read_b128 a[144:147], v234 offset:46080
	s_waitcnt lgkmcnt(3)
	v_mfma_f32_32x32x16_bf16 a[48:63], a[148:151], v[52:55], a[48:63]
	v_mfma_f32_32x32x16_bf16 a[64:79], a[148:151], v[120:123], a[64:79]
	ds_read_b128 a[148:151], v234 offset:46112
	s_waitcnt lgkmcnt(3)
	v_mfma_f32_32x32x16_bf16 a[48:63], a[152:155], v[56:59], a[48:63]
	v_mfma_f32_32x32x16_bf16 a[64:79], a[152:155], v[124:127], a[64:79]
	ds_read_b128 a[152:155], v234 offset:46144
	s_waitcnt lgkmcnt(3)
	v_mfma_f32_32x32x16_bf16 a[48:63], a[156:159], v[60:63], a[48:63]
	v_mfma_f32_32x32x16_bf16 a[64:79], a[156:159], v[130:133], a[64:79]
	ds_read_b128 a[156:159], v234 offset:46176
	s_waitcnt lgkmcnt(3)
	v_mfma_f32_32x32x16_bf16 a[80:95], a[144:147], v[48:51], a[80:95]
	v_mfma_f32_32x32x16_bf16 a[96:111], a[144:147], v[116:119], a[96:111]
	ds_read_b128 a[144:147], v234 offset:50688
	s_waitcnt lgkmcnt(3)
	v_mfma_f32_32x32x16_bf16 a[80:95], a[148:151], v[52:55], a[80:95]
	v_mfma_f32_32x32x16_bf16 a[96:111], a[148:151], v[120:123], a[96:111]
	ds_read_b128 a[148:151], v234 offset:50720
	s_waitcnt lgkmcnt(3)
	v_mfma_f32_32x32x16_bf16 a[80:95], a[152:155], v[56:59], a[80:95]
	v_mfma_f32_32x32x16_bf16 a[96:111], a[152:155], v[124:127], a[96:111]
	ds_read_b128 a[152:155], v234 offset:50752
	s_waitcnt lgkmcnt(3)
	v_mfma_f32_32x32x16_bf16 a[80:95], a[156:159], v[60:63], a[80:95]
	v_mfma_f32_32x32x16_bf16 a[96:111], a[156:159], v[130:133], a[96:111]
	ds_read_b128 a[156:159], v234 offset:50784
	s_waitcnt lgkmcnt(3)
	v_mfma_f32_32x32x16_bf16 a[32:47], a[144:147], v[48:51], a[32:47]
	v_mfma_f32_32x32x16_bf16 a[16:31], a[144:147], v[116:119], a[16:31]
	s_waitcnt lgkmcnt(2)
	v_mfma_f32_32x32x16_bf16 a[32:47], a[148:151], v[52:55], a[32:47]
	v_mfma_f32_32x32x16_bf16 a[16:31], a[148:151], v[120:123], a[16:31]
	s_waitcnt lgkmcnt(1)
	v_mfma_f32_32x32x16_bf16 a[32:47], a[152:155], v[56:59], a[32:47]
	v_mfma_f32_32x32x16_bf16 a[16:31], a[152:155], v[124:127], a[16:31]
	s_waitcnt lgkmcnt(0)
	v_mfma_f32_32x32x16_bf16 a[32:47], a[156:159], v[60:63], a[32:47]
	v_mfma_f32_32x32x16_bf16 a[16:31], a[156:159], v[130:133], a[16:31]
	s_bitcmp1_b32 s4, 0
	s_cselect_b32 s4, 0x4800, 0
	v_add_u32_e32 v48, s4, v128
	s_waitcnt lgkmcnt(0)
	s_barrier
	ds_read_b128 v[32:35], v48
	ds_read_b128 v[36:39], v48 offset:32
	s_waitcnt lgkmcnt(1)
	v_mfma_f32_32x32x16_bf16 a[186:201], v[32:35], v[28:31], a[0:15]
	v_add_u32_e32 v83, s4, v150
	v_mfma_f32_32x32x16_bf16 a[144:159], v[32:35], v[12:15], a[0:15]
	s_waitcnt lgkmcnt(0)
	v_mfma_f32_32x32x16_bf16 a[186:201], v[36:39], v[24:27], a[186:201]
	v_mfma_f32_32x32x16_bf16 a[144:159], v[36:39], v[8:11], a[144:159]
	ds_read_b128 v[32:35], v48 offset:64
	ds_read_b128 v[36:39], v48 offset:96
	s_waitcnt lgkmcnt(1)
	v_mfma_f32_32x32x16_bf16 a[186:201], v[32:35], v[20:23], a[186:201]
	s_waitcnt lgkmcnt(0)
	v_mfma_f32_32x32x16_bf16 a[186:201], v[36:39], v[16:19], a[186:201]
	v_mfma_f32_32x32x16_bf16 a[144:159], v[32:35], v[4:7], a[144:159]
	ds_read_b128 v[32:35], v48 offset:4608
	ds_read_b128 v[40:43], v48 offset:4640
	ds_read_b128 v[44:47], v48 offset:4672
	ds_read_b128 v[48:51], v48 offset:4704
	s_nop 6
	v_accvgpr_read_b32 v52, a186
	v_accvgpr_read_b32 v53, a187
	v_accvgpr_read_b32 v54, a188
	v_exp_f32_e32 v52, v52
	v_exp_f32_e32 v53, v53
	s_waitcnt lgkmcnt(3)
	v_mfma_f32_32x32x16_bf16 a[172:187], v[32:35], v[28:31], a[0:15]
	v_accvgpr_read_b32 v28, a189
	v_exp_f32_e32 v55, v28
	v_accvgpr_read_b32 v28, a190
	v_exp_f32_e32 v56, v28
	v_accvgpr_read_b32 v28, a191
	v_exp_f32_e32 v54, v54
	v_exp_f32_e32 v57, v28
	s_waitcnt lgkmcnt(2)
	v_mfma_f32_32x32x16_bf16 a[172:187], v[40:43], v[24:27], a[172:187]
	v_accvgpr_read_b32 v24, a192
	v_exp_f32_e32 v58, v24
	v_accvgpr_read_b32 v24, a193
	v_exp_f32_e32 v59, v24
	v_accvgpr_read_b32 v24, a194
	v_exp_f32_e32 v60, v24
	v_accvgpr_read_b32 v24, a195
	s_waitcnt lgkmcnt(1)
	v_mfma_f32_32x32x16_bf16 a[172:187], v[44:47], v[20:23], a[172:187]
	v_accvgpr_read_b32 v20, a196
	v_exp_f32_e32 v62, v20
	v_accvgpr_read_b32 v20, a197
	v_exp_f32_e32 v63, v20
	v_accvgpr_read_b32 v20, a198
	v_exp_f32_e32 v64, v20
	v_exp_f32_e32 v61, v24
	s_waitcnt lgkmcnt(0)
	v_mfma_f32_32x32x16_bf16 a[172:187], v[48:51], v[16:19], a[172:187]
	v_accvgpr_read_b32 v16, a199
	v_exp_f32_e32 v65, v16
	v_accvgpr_read_b32 v16, a200
	v_exp_f32_e32 v66, v16
	v_accvgpr_read_b32 v16, a201
	v_exp_f32_e32 v67, v16
	ds_read_b128 v[28:31], v83 offset:36928
	v_mfma_f32_32x32x16_bf16 a[144:159], v[36:39], v[0:3], a[144:159]
	s_nop 3
	v_accvgpr_read_b32 v16, a172
	v_exp_f32_e32 v36, v16
	v_accvgpr_read_b32 v16, a173
	v_exp_f32_e32 v37, v16
	v_accvgpr_read_b32 v16, a174
	v_exp_f32_e32 v38, v16
	v_accvgpr_read_b32 v16, a175
	v_mfma_f32_32x32x16_bf16 a[160:175], v[32:35], v[12:15], a[0:15]
	v_exp_f32_e32 v39, v16
	v_accvgpr_read_b32 v16, a144
	v_accvgpr_read_b32 v12, a176
	v_exp_f32_e32 v68, v12
	v_accvgpr_read_b32 v12, a177
	v_accvgpr_read_b32 v20, a157
	v_exp_f32_e32 v69, v12
	v_mfma_f32_32x32x16_bf16 a[160:175], v[40:43], v[8:11], a[160:175]
	v_accvgpr_read_b32 v12, a178
	v_exp_f32_e32 v84, v20
	v_accvgpr_read_b32 v20, a158
	v_exp_f32_e32 v70, v12
	v_accvgpr_read_b32 v12, a179
	v_exp_f32_e32 v85, v20
	v_accvgpr_read_b32 v20, a159
	v_mfma_f32_32x32x16_bf16 a[160:175], v[44:47], v[4:7], a[160:175]
	v_exp_f32_e32 v40, v12
	v_cvt_pk_bf16_f32 v12, v52, v53
	v_cvt_pk_bf16_f32 v13, v54, v55
	v_cvt_pk_bf16_f32 v14, v56, v57
	v_cvt_pk_bf16_f32 v15, v58, v59
	v_exp_f32_e32 v86, v20
	ds_read_b128 v[20:23], v83 offset:36896
	v_mfma_f32_32x32x16_bf16 a[160:175], v[48:51], v[0:3], a[160:175]
	v_exp_f32_e32 v49, v16
	v_accvgpr_read_b32 v16, a145
	v_exp_f32_e32 v50, v16
	v_accvgpr_read_b32 v16, a146
	v_exp_f32_e32 v51, v16
	v_accvgpr_read_b32 v16, a147
	v_exp_f32_e32 v71, v16
	v_accvgpr_read_b32 v16, a148
	v_exp_f32_e32 v72, v16
	v_accvgpr_read_b32 v16, a149
	v_exp_f32_e32 v73, v16
	v_accvgpr_read_b32 v16, a150
	v_exp_f32_e32 v74, v16
	v_accvgpr_read_b32 v16, a151
	v_exp_f32_e32 v75, v16
	v_accvgpr_read_b32 v16, a152
	v_exp_f32_e32 v76, v16
	v_accvgpr_read_b32 v16, a153
	v_exp_f32_e32 v77, v16
	v_accvgpr_read_b32 v16, a154
	v_exp_f32_e32 v78, v16
	v_accvgpr_read_b32 v16, a155
	v_exp_f32_e32 v79, v16
	v_accvgpr_read_b32 v16, a156
	v_exp_f32_e32 v82, v16
	ds_read_b128 v[16:19], v83 offset:36864
	v_accvgpr_read_b32 v24, a160
	v_exp_f32_e32 v87, v24
	v_accvgpr_read_b32 v24, a161
	v_exp_f32_e32 v88, v24
	v_cvt_pk_bf16_f32 v24, v49, v50
	v_cvt_pk_bf16_f32 v25, v51, v71
	v_cvt_pk_bf16_f32 v26, v72, v73
	v_cvt_pk_bf16_f32 v27, v74, v75
	s_waitcnt lgkmcnt(0)
	v_mfma_f32_32x32x16_bf16 a[144:159], v[16:19], v[12:15], a[128:143]
	v_accvgpr_read_b32 v8, a180
	v_exp_f32_e32 v41, v8
	v_accvgpr_read_b32 v8, a181
	v_exp_f32_e32 v42, v8
	v_accvgpr_read_b32 v8, a182
	v_exp_f32_e32 v43, v8
	v_cvt_pk_bf16_f32 v8, v60, v61
	v_mfma_f32_32x32x16_bf16 a[128:143], v[16:19], v[24:27], a[112:127]
	v_accvgpr_read_b32 v16, a162
	v_exp_f32_e32 v89, v16
	v_accvgpr_read_b32 v16, a163
	v_exp_f32_e32 v90, v16
	v_accvgpr_read_b32 v16, a164
	v_exp_f32_e32 v91, v16
	v_accvgpr_read_b32 v16, a165
	v_cvt_pk_bf16_f32 v9, v62, v63
	v_cvt_pk_bf16_f32 v10, v64, v65
	v_cvt_pk_bf16_f32 v11, v66, v67
	v_exp_f32_e32 v92, v16
	v_cvt_pk_bf16_f32 v16, v76, v77
	v_cvt_pk_bf16_f32 v17, v78, v79
	v_cvt_pk_bf16_f32 v18, v82, v84
	v_cvt_pk_bf16_f32 v19, v85, v86
	v_mfma_f32_32x32x16_bf16 a[144:159], v[20:23], v[8:11], a[144:159]
	v_accvgpr_read_b32 v32, a166
	v_accvgpr_read_b32 v4, a183
	v_exp_f32_e32 v93, v32
	v_exp_f32_e32 v44, v4
	v_accvgpr_read_b32 v4, a184
	v_exp_f32_e32 v45, v4
	v_accvgpr_read_b32 v4, a185
	v_mfma_f32_32x32x16_bf16 a[128:143], v[20:23], v[16:19], a[128:143]
	v_accvgpr_read_b32 v20, a167
	v_exp_f32_e32 v94, v20
	v_accvgpr_read_b32 v32, a169
	v_exp_f32_e32 v46, v4
	v_accvgpr_read_b32 v4, a186
	v_exp_f32_e32 v96, v32
	v_accvgpr_read_b32 v32, a170
	v_exp_f32_e32 v47, v4
	v_cvt_pk_bf16_f32 v4, v36, v37
	v_cvt_pk_bf16_f32 v5, v38, v39
	v_cvt_pk_bf16_f32 v6, v68, v69
	v_cvt_pk_bf16_f32 v7, v70, v40
	v_accvgpr_read_b32 v20, a168
	v_exp_f32_e32 v97, v32
	v_cvt_pk_bf16_f32 v32, v87, v88
	v_cvt_pk_bf16_f32 v33, v89, v90
	v_cvt_pk_bf16_f32 v34, v91, v92
	v_cvt_pk_bf16_f32 v35, v93, v94
	v_exp_f32_e32 v95, v20
	ds_read_b128 v[20:23], v83 offset:36960
	v_mfma_f32_32x32x16_bf16 a[144:159], v[28:31], v[4:7], a[144:159]
	v_accvgpr_read_b32 v0, a187
	v_exp_f32_e32 v48, v0
	v_cvt_pk_bf16_f32 v0, v41, v42
	v_cvt_pk_bf16_f32 v1, v43, v44
	v_cvt_pk_bf16_f32 v2, v45, v46
	v_cvt_pk_bf16_f32 v3, v47, v48
	v_cvt_pk_bf16_f32 v130, v95, v96
	v_mfma_f32_32x32x16_bf16 a[128:143], v[28:31], v[32:35], a[128:143]
	v_accvgpr_read_b32 v28, a171
	v_exp_f32_e32 v98, v28
	v_accvgpr_read_b32 v28, a172
	v_exp_f32_e32 v99, v28
	v_accvgpr_read_b32 v28, a173
	v_exp_f32_e32 v100, v28
	v_accvgpr_read_b32 v28, a174
	v_exp_f32_e32 v101, v28
	v_accvgpr_read_b32 v28, a175
	v_exp_f32_e32 v102, v28
	v_cvt_pk_bf16_f32 v131, v97, v98
	v_cvt_pk_bf16_f32 v132, v99, v100
	s_waitcnt lgkmcnt(0)
	v_mfma_f32_32x32x16_bf16 a[144:159], v[20:23], v[0:3], a[144:159]
	v_cvt_pk_bf16_f32 v133, v101, v102
	s_nop 1
	v_mfma_f32_32x32x16_bf16 a[128:143], v[20:23], v[130:133], a[128:143]
	ds_read_b128 v[20:23], v83 offset:41472
	ds_read_b128 v[28:31], v83 offset:41504
	s_nop 5
	v_accvgpr_read_b32 v112, a144
	v_accvgpr_read_b32 v113, a145
	v_accvgpr_read_b32 v114, a146
	v_accvgpr_read_b32 v115, a147
	s_waitcnt lgkmcnt(1)
	v_mfma_f32_32x32x16_bf16 a[112:127], v[20:23], v[12:15], a[48:63]
	v_accvgpr_read_b32 v116, a148
	v_accvgpr_read_b32 v117, a149
	v_accvgpr_read_b32 v118, a150
	v_accvgpr_read_b32 v119, a151
	v_accvgpr_read_b32 v120, a152
	v_accvgpr_read_b32 v121, a153
	v_accvgpr_read_b32 v122, a154
	v_mfma_f32_32x32x16_bf16 a[48:63], v[20:23], v[24:27], a[64:79]
	v_accvgpr_read_b32 v123, a155
	v_accvgpr_read_b32 v124, a156
	v_accvgpr_read_b32 v125, a157
	v_accvgpr_read_b32 v126, a158
	v_accvgpr_read_b32 v127, a159
	s_waitcnt lgkmcnt(0)
	v_mfma_f32_32x32x16_bf16 a[112:127], v[28:31], v[8:11], a[112:127]
	v_mfma_f32_32x32x16_bf16 a[48:63], v[28:31], v[16:19], a[48:63]
	ds_read_b128 v[20:23], v83 offset:41536
	ds_read_b128 v[28:31], v83 offset:41568
	s_waitcnt lgkmcnt(1)
	v_mfma_f32_32x32x16_bf16 a[112:127], v[20:23], v[4:7], a[112:127]
	v_mfma_f32_32x32x16_bf16 a[48:63], v[20:23], v[32:35], a[48:63]
	s_waitcnt lgkmcnt(0)
	v_mfma_f32_32x32x16_bf16 a[112:127], v[28:31], v[0:3], a[112:127]
	v_mfma_f32_32x32x16_bf16 a[48:63], v[28:31], v[130:133], a[48:63]
	ds_read_b128 v[20:23], v83 offset:46080
	ds_read_b128 v[28:31], v83 offset:46112
	s_waitcnt lgkmcnt(1)
	v_mfma_f32_32x32x16_bf16 a[64:79], v[20:23], v[12:15], a[80:95]
	v_mfma_f32_32x32x16_bf16 a[80:95], v[20:23], v[24:27], a[96:111]
	ds_read_b128 v[20:23], v83 offset:46144
	s_waitcnt lgkmcnt(1)
	v_mfma_f32_32x32x16_bf16 a[64:79], v[28:31], v[8:11], a[64:79]
	v_mfma_f32_32x32x16_bf16 a[80:95], v[28:31], v[16:19], a[80:95]
	v_add_f32_e32 v28, 0, v52
	v_add_f32_e32 v28, v53, v28
	v_add_f32_e32 v28, v54, v28
	v_add_f32_e32 v28, v55, v28
	v_add_f32_e32 v52, v56, v28
	v_add_f32_e32 v52, v57, v52
	v_add_f32_e32 v52, v58, v52
	v_add_f32_e32 v52, v59, v52
	v_add_f32_e32 v52, v60, v52
	v_add_f32_e32 v52, v61, v52
	v_add_f32_e32 v52, v62, v52
	v_add_f32_e32 v52, v63, v52
	ds_read_b128 v[28:31], v83 offset:46176
	s_waitcnt lgkmcnt(1)
	v_mfma_f32_32x32x16_bf16 a[64:79], v[20:23], v[4:7], a[64:79]
	v_mfma_f32_32x32x16_bf16 a[80:95], v[20:23], v[32:35], a[80:95]
	v_add_f32_e32 v20, v64, v52
	v_add_f32_e32 v20, v65, v20
	v_add_f32_e32 v20, v66, v20
	v_add_f32_e32 v20, v67, v20
	v_add_f32_e32 v20, v36, v20
	v_add_f32_e32 v20, v37, v20
	v_add_f32_e32 v20, v38, v20
	v_add_f32_e32 v20, v39, v20
	v_add_f32_e32 v20, v68, v20
	v_add_f32_e32 v20, v69, v20
	v_add_f32_e32 v20, v70, v20
	v_add_f32_e32 v20, v40, v20
	v_add_f32_e32 v36, v41, v20
	ds_read_b128 v[20:23], v83 offset:50688
	s_waitcnt lgkmcnt(1)
	v_mfma_f32_32x32x16_bf16 a[64:79], v[28:31], v[0:3], a[64:79]
	v_mfma_f32_32x32x16_bf16 a[80:95], v[28:31], v[130:133], a[80:95]
	v_add_f32_e32 v28, v42, v36
	v_add_f32_e32 v28, v43, v28
	v_add_f32_e32 v28, v44, v28
	v_add_f32_e32 v28, v45, v28
	v_add_f32_e32 v28, v46, v28
	v_add_f32_e32 v36, v47, v28
	ds_read_b128 v[28:31], v83 offset:50720
	s_waitcnt lgkmcnt(1)
	v_mfma_f32_32x32x16_bf16 a[96:111], v[20:23], v[12:15], a[32:47]
	v_add_f32_e32 v12, v48, v36
	v_add_f32_e32 v136, v81, v12
	v_add_f32_e32 v12, 0, v49
	v_add_f32_e32 v12, v50, v12
	v_add_f32_e32 v12, v51, v12
	v_add_f32_e32 v12, v71, v12
	v_add_f32_e32 v12, v72, v12
	v_add_f32_e32 v12, v73, v12
	v_add_f32_e32 v12, v74, v12
	v_add_f32_e32 v12, v75, v12
	v_add_f32_e32 v12, v76, v12
	v_add_f32_e32 v12, v77, v12
	v_add_f32_e32 v12, v78, v12
	v_add_f32_e32 v12, v79, v12
	s_waitcnt lgkmcnt(0)
	v_mfma_f32_32x32x16_bf16 a[96:111], v[28:31], v[8:11], a[96:111]
	v_add_f32_e32 v8, v82, v12
	v_add_f32_e32 v8, v84, v8
	v_add_f32_e32 v8, v85, v8
	v_add_f32_e32 v8, v86, v8
	v_add_f32_e32 v8, v87, v8
	v_add_f32_e32 v12, v88, v8
	ds_read_b128 v[8:11], v83 offset:50752
	v_mfma_f32_32x32x16_bf16 a[32:47], v[20:23], v[24:27], a[16:31]
	v_add_f32_e32 v12, v89, v12
	v_add_f32_e32 v12, v90, v12
	v_add_f32_e32 v12, v91, v12
	v_add_f32_e32 v12, v92, v12
	v_add_f32_e32 v12, v93, v12
	v_accvgpr_read_b32 v48, a128
	v_accvgpr_read_b32 v49, a129
	v_mfma_f32_32x32x16_bf16 a[32:47], v[28:31], v[16:19], a[32:47]
	v_add_f32_e32 v16, v94, v12
	ds_read_b128 v[12:15], v83 offset:50784
	v_accvgpr_read_b32 v50, a130
	v_accvgpr_read_b32 v51, a131
	v_accvgpr_read_b32 v52, a132
	v_accvgpr_read_b32 v53, a133
	v_accvgpr_read_b32 v54, a134
	s_waitcnt lgkmcnt(1)
	v_mfma_f32_32x32x16_bf16 a[96:111], v[8:11], v[4:7], a[96:111]
	v_add_f32_e32 v4, v95, v16
	v_add_f32_e32 v4, v96, v4
	v_add_f32_e32 v4, v97, v4
	v_add_f32_e32 v4, v98, v4
	v_add_f32_e32 v4, v99, v4
	v_add_f32_e32 v4, v100, v4
	v_add_f32_e32 v4, v101, v4
	v_add_f32_e32 v4, v102, v4
	v_add_f32_e32 v137, v80, v4
	ds_bpermute_b32 v4, v159, v136
	v_mfma_f32_32x32x16_bf16 a[32:47], v[8:11], v[32:35], a[32:47]
	v_accvgpr_read_b32 v96, a112
	v_accvgpr_read_b32 v32, a48
	v_accvgpr_read_b32 v95, a79
	s_waitcnt lgkmcnt(0)
	v_add_f32_e32 v136, v136, v4
	v_div_scale_f32 v140, s[60:61], v136, v136, 1.0
	v_rcp_f32_e32 v141, v140
	v_mfma_f32_32x32x16_bf16 a[32:47], v[12:15], v[130:133], a[32:47]
	ds_bpermute_b32 v131, v159, v137
	v_accvgpr_read_b32 v16, a80
	v_fma_f32 v130, -v140, v141, 1.0
	v_fmac_f32_e32 v141, v130, v141
	v_div_scale_f32 v130, vcc, 1.0, v136, 1.0
	v_mul_f32_e32 v132, v130, v141
	v_fma_f32 v133, -v140, v132, v130
	s_waitcnt lgkmcnt(0)
	v_add_f32_e32 v131, v137, v131
	v_fmac_f32_e32 v132, v133, v141
	v_div_scale_f32 v133, s[60:61], v131, v131, 1.0
	v_rcp_f32_e32 v137, v133
	v_mfma_f32_32x32x16_bf16 a[96:111], v[12:15], v[0:3], a[96:111]
	v_fma_f32 v130, -v140, v132, v130
	v_div_fmas_f32 v130, v130, v141, v132
	v_div_fixup_f32 v222, v130, v136, 1.0
	v_fma_f32 v130, -v133, v137, 1.0
	v_fmac_f32_e32 v137, v130, v137
	v_div_scale_f32 v130, vcc, 1.0, v131, 1.0
	v_mul_f32_e32 v132, v130, v137
	v_fma_f32 v136, -v133, v132, v130
	v_fmac_f32_e32 v132, v136, v137
	v_fma_f32 v130, -v133, v132, v130
	v_accvgpr_read_b32 v0, a32
	s_nop 0
	v_accvgpr_read_b32 v64, a96
	v_div_fmas_f32 v130, v130, v137, v132
	v_accvgpr_read_b32 v55, a135
	v_accvgpr_read_b32 v56, a136
	v_accvgpr_read_b32 v57, a137
	v_accvgpr_read_b32 v58, a138
	v_accvgpr_read_b32 v59, a139
	v_accvgpr_read_b32 v60, a140
	v_accvgpr_read_b32 v61, a141
	v_accvgpr_read_b32 v62, a142
	v_accvgpr_read_b32 v63, a143
	v_accvgpr_read_b32 v97, a113
	v_accvgpr_read_b32 v98, a114
	v_accvgpr_read_b32 v99, a115
	v_accvgpr_read_b32 v100, a116
	v_accvgpr_read_b32 v101, a117
	v_accvgpr_read_b32 v102, a118
	v_accvgpr_read_b32 v103, a119
	v_accvgpr_read_b32 v104, a120
	v_accvgpr_read_b32 v105, a121
	v_accvgpr_read_b32 v106, a122
	v_accvgpr_read_b32 v107, a123
	v_accvgpr_read_b32 v108, a124
	v_accvgpr_read_b32 v109, a125
	v_accvgpr_read_b32 v110, a126
	v_accvgpr_read_b32 v111, a127
	v_accvgpr_read_b32 v33, a49
	v_accvgpr_read_b32 v34, a50
	v_accvgpr_read_b32 v35, a51
	v_accvgpr_read_b32 v36, a52
	v_accvgpr_read_b32 v37, a53
	v_accvgpr_read_b32 v38, a54
	v_accvgpr_read_b32 v39, a55
	v_accvgpr_read_b32 v40, a56
	v_accvgpr_read_b32 v41, a57
	v_accvgpr_read_b32 v42, a58
	v_accvgpr_read_b32 v43, a59
	v_accvgpr_read_b32 v44, a60
	v_accvgpr_read_b32 v45, a61
	v_accvgpr_read_b32 v46, a62
	v_accvgpr_read_b32 v47, a63
	v_accvgpr_read_b32 v94, a78
	v_accvgpr_read_b32 v93, a77
	v_accvgpr_read_b32 v92, a76
	v_accvgpr_read_b32 v91, a75
	v_accvgpr_read_b32 v90, a74
	v_accvgpr_read_b32 v89, a73
	v_accvgpr_read_b32 v88, a72
	v_accvgpr_read_b32 v87, a71
	v_accvgpr_read_b32 v86, a70
	v_accvgpr_read_b32 v85, a69
	v_accvgpr_read_b32 v84, a68
	v_accvgpr_read_b32 v83, a67
	v_accvgpr_read_b32 v82, a66
	v_accvgpr_read_b32 v81, a65
	v_accvgpr_read_b32 v80, a64
	v_accvgpr_read_b32 v17, a81
	v_accvgpr_read_b32 v18, a82
	v_accvgpr_read_b32 v19, a83
	v_accvgpr_read_b32 v20, a84
	v_accvgpr_read_b32 v21, a85
	v_accvgpr_read_b32 v22, a86
	v_accvgpr_read_b32 v23, a87
	v_accvgpr_read_b32 v24, a88
	v_accvgpr_read_b32 v25, a89
	v_accvgpr_read_b32 v26, a90
	v_accvgpr_read_b32 v27, a91
	v_accvgpr_read_b32 v28, a92
	v_accvgpr_read_b32 v29, a93
	v_accvgpr_read_b32 v30, a94
	v_accvgpr_read_b32 v31, a95
	v_accvgpr_read_b32 v65, a97
	v_accvgpr_read_b32 v66, a98
	v_accvgpr_read_b32 v67, a99
	v_accvgpr_read_b32 v68, a100
	v_accvgpr_read_b32 v69, a101
	v_accvgpr_read_b32 v70, a102
	v_accvgpr_read_b32 v71, a103
	v_accvgpr_read_b32 v72, a104
	v_accvgpr_read_b32 v73, a105
	v_accvgpr_read_b32 v74, a106
	v_accvgpr_read_b32 v75, a107
	v_accvgpr_read_b32 v76, a108
	v_accvgpr_read_b32 v77, a109
	v_accvgpr_read_b32 v78, a110
	v_accvgpr_read_b32 v79, a111
	v_accvgpr_read_b32 v1, a33
	v_accvgpr_read_b32 v2, a34
	v_accvgpr_read_b32 v3, a35
	v_accvgpr_read_b32 v4, a36
	v_accvgpr_read_b32 v5, a37
	v_accvgpr_read_b32 v6, a38
	v_accvgpr_read_b32 v7, a39
	v_accvgpr_read_b32 v8, a40
	v_accvgpr_read_b32 v9, a41
	v_accvgpr_read_b32 v10, a42
	v_accvgpr_read_b32 v11, a43
	v_accvgpr_read_b32 v12, a44
	v_accvgpr_read_b32 v13, a45
	v_accvgpr_read_b32 v14, a46
	v_accvgpr_read_b32 v15, a47
	v_div_fixup_f32 v168, v130, v131, 1.0
	s_barrier
	s_and_saveexec_b64 s[60:61], s[6:7]
	s_cbranch_execz .LBB0_2274
	v_accvgpr_read_b32 v133, a216
	v_mul_f32_e32 v130, v133, v222
	v_mul_f32_e32 v131, v112, v130
	v_mul_f32_e32 v132, v113, v130
	ds_write2st64_b32 v139, v131, v132 offset1:1
	v_mul_f32_e32 v131, v114, v130
	v_mul_f32_e32 v132, v115, v130
	ds_write2st64_b32 v139, v131, v132 offset0:2 offset1:3
	v_mul_f32_e32 v131, v116, v130
	v_mul_f32_e32 v132, v117, v130
	ds_write2st64_b32 v139, v131, v132 offset0:4 offset1:5
	v_mul_f32_e32 v131, v118, v130
	v_mul_f32_e32 v132, v119, v130
	ds_write2st64_b32 v139, v131, v132 offset0:6 offset1:7
	v_mul_f32_e32 v131, v120, v130
	v_mul_f32_e32 v132, v121, v130
	ds_write2st64_b32 v139, v131, v132 offset0:8 offset1:9
	v_mul_f32_e32 v131, v122, v130
	v_mul_f32_e32 v132, v123, v130
	ds_write2st64_b32 v139, v131, v132 offset0:10 offset1:11
	v_mul_f32_e32 v131, v124, v130
	v_mul_f32_e32 v132, v125, v130
	ds_write2st64_b32 v139, v131, v132 offset0:12 offset1:13
	v_mul_f32_e32 v131, v126, v130
	v_mul_f32_e32 v132, v127, v130
	ds_write2st64_b32 v139, v131, v132 offset0:14 offset1:15
	v_mul_f32_e32 v131, v96, v130
	v_mul_f32_e32 v132, v97, v130
	ds_write2st64_b32 v139, v131, v132 offset0:16 offset1:17
	v_mul_f32_e32 v131, v98, v130
	v_mul_f32_e32 v132, v99, v130
	ds_write2st64_b32 v139, v131, v132 offset0:18 offset1:19
	v_mul_f32_e32 v131, v100, v130
	v_mul_f32_e32 v132, v101, v130
	ds_write2st64_b32 v139, v131, v132 offset0:20 offset1:21
	v_mul_f32_e32 v131, v102, v130
	v_mul_f32_e32 v132, v103, v130
	ds_write2st64_b32 v139, v131, v132 offset0:22 offset1:23
	v_mul_f32_e32 v131, v104, v130
	v_mul_f32_e32 v132, v105, v130
	ds_write2st64_b32 v139, v131, v132 offset0:24 offset1:25
	v_mul_f32_e32 v131, v106, v130
	v_mul_f32_e32 v132, v107, v130
	ds_write2st64_b32 v139, v131, v132 offset0:26 offset1:27
	v_mul_f32_e32 v131, v108, v130
	v_mul_f32_e32 v132, v109, v130
	ds_write2st64_b32 v139, v131, v132 offset0:28 offset1:29
	v_mul_f32_e32 v131, v110, v130
	v_mul_f32_e32 v132, v111, v130
	ds_write2st64_b32 v139, v131, v132 offset0:30 offset1:31
	v_mul_f32_e32 v131, v80, v130
	v_mul_f32_e32 v132, v81, v130
	ds_write2st64_b32 v139, v131, v132 offset0:32 offset1:33
	v_mul_f32_e32 v131, v82, v130
	v_mul_f32_e32 v132, v83, v130
	ds_write2st64_b32 v139, v131, v132 offset0:34 offset1:35
	v_mul_f32_e32 v131, v84, v130
	v_mul_f32_e32 v132, v85, v130
	ds_write2st64_b32 v139, v131, v132 offset0:36 offset1:37
	v_mul_f32_e32 v131, v86, v130
	v_mul_f32_e32 v132, v87, v130
	ds_write2st64_b32 v139, v131, v132 offset0:38 offset1:39
	v_mul_f32_e32 v131, v88, v130
	v_mul_f32_e32 v132, v89, v130
	ds_write2st64_b32 v139, v131, v132 offset0:40 offset1:41
	v_mul_f32_e32 v131, v90, v130
	v_mul_f32_e32 v132, v91, v130
	ds_write2st64_b32 v139, v131, v132 offset0:42 offset1:43
	v_mul_f32_e32 v131, v92, v130
	v_mul_f32_e32 v132, v93, v130
	ds_write2st64_b32 v139, v131, v132 offset0:44 offset1:45
	v_mul_f32_e32 v131, v94, v130
	v_mul_f32_e32 v132, v95, v130
	ds_write2st64_b32 v139, v131, v132 offset0:46 offset1:47
	v_mul_f32_e32 v131, v64, v130
	v_mul_f32_e32 v132, v65, v130
	ds_write2st64_b32 v139, v131, v132 offset0:48 offset1:49
	v_mul_f32_e32 v131, v66, v130
	v_mul_f32_e32 v132, v67, v130
	ds_write2st64_b32 v139, v131, v132 offset0:50 offset1:51
	v_mul_f32_e32 v131, v68, v130
	v_mul_f32_e32 v132, v69, v130
	ds_write2st64_b32 v139, v131, v132 offset0:52 offset1:53
	v_mul_f32_e32 v131, v70, v130
	v_mul_f32_e32 v132, v71, v130
	ds_write2st64_b32 v139, v131, v132 offset0:54 offset1:55
	v_mul_f32_e32 v131, v72, v130
	v_mul_f32_e32 v132, v73, v130
	ds_write2st64_b32 v139, v131, v132 offset0:56 offset1:57
	v_mul_f32_e32 v131, v74, v130
	v_mul_f32_e32 v132, v75, v130
	ds_write2st64_b32 v139, v131, v132 offset0:58 offset1:59
	v_mul_f32_e32 v131, v76, v130
	v_mul_f32_e32 v132, v77, v130
	ds_write2st64_b32 v139, v131, v132 offset0:60 offset1:61
	v_mul_f32_e32 v131, v78, v130
	v_mul_f32_e32 v130, v79, v130
	ds_write2st64_b32 v139, v131, v130 offset0:62 offset1:63
	v_mul_f32_e32 v130, v133, v168
	v_mul_f32_e32 v131, v48, v130
	v_mul_f32_e32 v132, v49, v130
	ds_write2st64_b32 v254, v131, v132 offset1:1
	v_mul_f32_e32 v131, v50, v130
	v_mul_f32_e32 v132, v51, v130
	ds_write2st64_b32 v254, v131, v132 offset0:2 offset1:3
	v_mul_f32_e32 v131, v52, v130
	v_mul_f32_e32 v132, v53, v130
	ds_write2st64_b32 v254, v131, v132 offset0:4 offset1:5
	v_mul_f32_e32 v131, v54, v130
	v_mul_f32_e32 v132, v55, v130
	ds_write2st64_b32 v254, v131, v132 offset0:6 offset1:7
	v_mul_f32_e32 v131, v56, v130
	v_mul_f32_e32 v132, v57, v130
	ds_write2st64_b32 v254, v131, v132 offset0:8 offset1:9
	v_mul_f32_e32 v131, v58, v130
	v_mul_f32_e32 v132, v59, v130
	ds_write2st64_b32 v254, v131, v132 offset0:10 offset1:11
	v_mul_f32_e32 v131, v60, v130
	v_mul_f32_e32 v132, v61, v130
	ds_write2st64_b32 v254, v131, v132 offset0:12 offset1:13
	v_mul_f32_e32 v131, v62, v130
	v_mul_f32_e32 v132, v63, v130
	ds_write2st64_b32 v254, v131, v132 offset0:14 offset1:15
	v_mul_f32_e32 v131, v32, v130
	v_mul_f32_e32 v132, v33, v130
	ds_write2st64_b32 v254, v131, v132 offset0:16 offset1:17
	v_mul_f32_e32 v131, v34, v130
	v_mul_f32_e32 v132, v35, v130
	ds_write2st64_b32 v254, v131, v132 offset0:18 offset1:19
	v_mul_f32_e32 v131, v36, v130
	v_mul_f32_e32 v132, v37, v130
	ds_write2st64_b32 v254, v131, v132 offset0:20 offset1:21
	v_mul_f32_e32 v131, v38, v130
	v_mul_f32_e32 v132, v39, v130
	ds_write2st64_b32 v254, v131, v132 offset0:22 offset1:23
	v_mul_f32_e32 v131, v40, v130
	v_mul_f32_e32 v132, v41, v130
	ds_write2st64_b32 v254, v131, v132 offset0:24 offset1:25
	v_mul_f32_e32 v131, v42, v130
	v_mul_f32_e32 v132, v43, v130
	ds_write2st64_b32 v254, v131, v132 offset0:26 offset1:27
	v_mul_f32_e32 v131, v44, v130
	v_mul_f32_e32 v132, v45, v130
	ds_write2st64_b32 v254, v131, v132 offset0:28 offset1:29
	v_mul_f32_e32 v131, v46, v130
	v_mul_f32_e32 v132, v47, v130
	ds_write2st64_b32 v254, v131, v132 offset0:30 offset1:31
	v_mul_f32_e32 v131, v16, v130
	v_mul_f32_e32 v132, v17, v130
	ds_write2st64_b32 v254, v131, v132 offset0:32 offset1:33
	v_mul_f32_e32 v131, v18, v130
	v_mul_f32_e32 v132, v19, v130
	ds_write2st64_b32 v254, v131, v132 offset0:34 offset1:35
	v_mul_f32_e32 v131, v20, v130
	v_mul_f32_e32 v132, v21, v130
	ds_write2st64_b32 v254, v131, v132 offset0:36 offset1:37
	v_mul_f32_e32 v131, v22, v130
	v_mul_f32_e32 v132, v23, v130
	ds_write2st64_b32 v254, v131, v132 offset0:38 offset1:39
	v_mul_f32_e32 v131, v24, v130
	v_mul_f32_e32 v132, v25, v130
	ds_write2st64_b32 v254, v131, v132 offset0:40 offset1:41
	v_mul_f32_e32 v131, v26, v130
	v_mul_f32_e32 v132, v27, v130
	ds_write2st64_b32 v254, v131, v132 offset0:42 offset1:43
	v_mul_f32_e32 v131, v28, v130
	v_mul_f32_e32 v132, v29, v130
	ds_write2st64_b32 v254, v131, v132 offset0:44 offset1:45
	v_mul_f32_e32 v131, v30, v130
	v_mul_f32_e32 v132, v31, v130
	ds_write2st64_b32 v254, v131, v132 offset0:46 offset1:47
	v_mul_f32_e32 v131, v0, v130
	v_mul_f32_e32 v132, v1, v130
	ds_write2st64_b32 v254, v131, v132 offset0:48 offset1:49
	v_mul_f32_e32 v131, v2, v130
	v_mul_f32_e32 v132, v3, v130
	ds_write2st64_b32 v254, v131, v132 offset0:50 offset1:51
	v_mul_f32_e32 v131, v4, v130
	v_mul_f32_e32 v132, v5, v130
	ds_write2st64_b32 v254, v131, v132 offset0:52 offset1:53
	v_mul_f32_e32 v131, v6, v130
	v_mul_f32_e32 v132, v7, v130
	ds_write2st64_b32 v254, v131, v132 offset0:54 offset1:55
	v_mul_f32_e32 v131, v8, v130
	v_mul_f32_e32 v132, v9, v130
	ds_write2st64_b32 v254, v131, v132 offset0:56 offset1:57
	v_mul_f32_e32 v131, v10, v130
	v_mul_f32_e32 v132, v11, v130
	ds_write2st64_b32 v254, v131, v132 offset0:58 offset1:59
	v_mul_f32_e32 v131, v12, v130
	v_mul_f32_e32 v132, v13, v130
	ds_write2st64_b32 v254, v131, v132 offset0:60 offset1:61
	v_mul_f32_e32 v131, v14, v130
	v_mul_f32_e32 v130, v15, v130
	ds_write2st64_b32 v254, v131, v130 offset0:62 offset1:63
